# rwkv_prep: lora weight-fragment loads and code-fragment loads batched (fresh registers, counted vmcnt)
# speedup vs baseline: 1.0878x; 1.0054x over previous
; __device__ __forceinline__ float lo16(unsigned u) { return __uint_as_float(u << 16); }
; __device__ __forceinline__ float hi16(unsigned u) { return __uint_as_float(u & 0xffff0000u); }
; __device__ __forceinline__ unsigned pk2(float lo, float hi) { f32x2n v = {lo, hi}; bf16x2n b = __builtin_convertvector(v, bf16x2n); return __builtin_bit_cast(unsigned, b); }
; __device__ __forceinline__ float sigm(float x) { return __builtin_amdgcn_rcpf(1.f + __expf(-x)); }
; __device__ __forceinline__ float tanh_fast(float x) { float e = __expf(2.f * x); return 1.f - 2.f * __builtin_amdgcn_rcpf(e + 1.f); }
; #define p (kparams())
; template <int MODE>
; __device__ __forceinline__ bf16x8 xf_frag(const bf16_t* p) {
;   const u32x4 u = *(const u32x4*)p;
;   if (MODE == 0) return __builtin_bit_cast(bf16x8, u);
;   float f[8] = {lo16(u.x), hi16(u.x), lo16(u.y), hi16(u.y), lo16(u.z), hi16(u.z), lo16(u.w), hi16(u.w)};
; #pragma unroll
;   for (int e = 0; e < 8; ++e) f[e] = MODE == 1 ? tanh_fast(f[e]) : sigm(f[e]);
;   u32x4 o; o.x = pk2(f[0], f[1]); o.y = pk2(f[2], f[3]); o.z = pk2(f[4], f[5]); o.w = pk2(f[6], f[7]);
;   return __builtin_bit_cast(bf16x8, o);
; __device__ __forceinline__ void rwkv_prep_item(const int wv_, KPR p, int l, int item, bf16_t* tile) {
;     ...
;   float inv[4];
; #pragma unroll
;   for (int j = 0; j < 4; ++j) { inv[j] = rsqrtf(rowsum16(ss[j]) + 1e-12f); const float r = rowsum16(rk[j]); if (cl == 0) RK[(size_t)(R0 + tq * 4 + j) * 8 + wid] = r; }
;   const bf16_t* arow = PNG + (size_t)(R0 + cl) * NNGP;
;   bf16x8 aw[2][2], aa[2][2], ag[4];
; #pragma unroll
;   for (int d = 0; d < 2; ++d)
; #pragma unroll
;     for (int ks = 0; ks < 2; ++ks) { aw[d][ks] = xf_frag<1>(arow + O_WL + d * 64 + ks * 32 + tq * 8); aa[d][ks] = xf_frag<0>(arow + O_AL + d * 64 + ks * 32 + tq * 8); }
; #pragma unroll
;   for (int ks = 0; ks < 4; ++ks) ag[ks] = xf_frag<2>(arow + O_GL + ks * 32 + tq * 8);
.LBB0_434:
	s_or_b64 exec, exec, s[18:19]
	v_add_f32_e32 v0, v1, v4
	v_add_f32_e32 v0, 0x2b8cbccc, v0
	v_cmp_gt_f32_e32 vcc, s96, v0
	v_mul_f32_e32 v1, 0x4b800000, v0
	v_or_b32_e32 v4, s24, v60
	v_cndmask_b32_e32 v0, v0, v1, vcc
	v_rsq_f32_e32 v0, v0
	v_lshlrev_b64 v[76:77], 10, v[52:53]
	v_lshlrev_b64 v[78:79], 10, v[54:55]
	v_lshlrev_b64 v[80:81], 10, v[56:57]
	v_mul_f32_e32 v1, 0x45800000, v0
	v_cndmask_b32_e32 v86, v0, v1, vcc
	v_add_f32_e32 v0, v5, v6
	v_add_f32_e32 v0, 0x2b8cbccc, v0
	v_cmp_gt_f32_e32 vcc, s96, v0
	v_mul_f32_e32 v1, 0x4b800000, v0
	v_lshlrev_b64 v[82:83], 10, v[58:59]
	v_cndmask_b32_e32 v0, v0, v1, vcc
	v_rsq_f32_e32 v0, v0
	v_add_u32_e32 v84, v61, v60
	s_mov_b32 s20, 0
	v_mul_f32_e32 v1, 0x45800000, v0
	v_cndmask_b32_e32 v87, v0, v1, vcc
	v_add_f32_e32 v0, v7, v8
	v_add_f32_e32 v0, 0x2b8cbccc, v0
	v_cmp_gt_f32_e32 vcc, s96, v0
	v_mul_f32_e32 v1, 0x4b800000, v0
	s_nop 0
	v_cndmask_b32_e32 v0, v0, v1, vcc
	v_rsq_f32_e32 v0, v0
	s_nop 0
	v_mul_f32_e32 v1, 0x45800000, v0
	v_cndmask_b32_e32 v88, v0, v1, vcc
	v_add_f32_e32 v0, v9, v13
	v_add_f32_e32 v0, 0x2b8cbccc, v0
	v_cmp_gt_f32_e32 vcc, s96, v0
	v_mul_f32_e32 v1, 0x4b800000, v0
	s_nop 0
	v_cndmask_b32_e32 v0, v0, v1, vcc
	v_rsq_f32_e32 v0, v0
	s_nop 0
	v_mul_f32_e32 v1, 0x45800000, v0
	v_cndmask_b32_e32 v89, v0, v1, vcc
	v_mov_b64_e32 v[0:1], s[16:17]
	v_mad_i64_i32 v[4:5], s[16:17], v4, s81, v[0:1]
	v_lshlrev_b32_e32 v0, 4, v12
	v_mov_b32_e32 v1, v2
	v_lshl_add_u64 v[48:49], v[4:5], 0, v[0:1]
	global_load_dwordx4 v[190:193], v[48:49], off offset:3072
	global_load_dwordx4 v[194:197], v[48:49], off offset:3328
	global_load_dwordx4 v[198:201], v[48:49], off offset:3136
	global_load_dwordx4 v[202:205], v[48:49], off offset:3392
	global_load_dwordx4 v[206:209], v[48:49], off offset:3200
	global_load_dwordx4 v[210:213], v[48:49], off offset:3456
	global_load_dwordx4 v[214:217], v[48:49], off offset:3264
	global_load_dwordx4 v[218:221], v[48:49], off offset:3520
	global_load_dwordx4 v[222:225], v[48:49], off offset:3584
	global_load_dwordx4 v[226:229], v[48:49], off offset:3648
	global_load_dwordx4 v[230:233], v[48:49], off offset:3712
	global_load_dwordx4 v[234:237], v[48:49], off offset:3776
	s_waitcnt vmcnt(11)
	v_mov_b64_e32 v[4:5], v[190:191]
	v_mov_b64_e32 v[6:7], v[192:193]
	s_add_u32 s16, s14, 0x2a2e0000
	s_addc_u32 s17, s15, 0
	v_lshlrev_b32_e32 v8, 16, v4
	v_and_b32_e32 v9, 0xffff0000, v4
	v_lshlrev_b32_e32 v10, 16, v5
	v_and_b32_e32 v11, 0xffff0000, v5
	v_lshlrev_b32_e32 v12, 16, v6
	v_and_b32_e32 v13, 0xffff0000, v6
	v_lshlrev_b32_e32 v14, 16, v7
	v_and_b32_e32 v15, 0xffff0000, v7
	v_add_f32_e32 v4, v8, v8
	v_add_f32_e32 v5, v9, v9
	v_add_f32_e32 v6, v10, v10
	v_add_f32_e32 v7, v11, v11
	v_add_f32_e32 v8, v12, v12
	v_add_f32_e32 v9, v13, v13
	v_add_f32_e32 v10, v14, v14
	v_add_f32_e32 v11, v15, v15
	v_mul_f32_e32 v4, 0x3fb8aa3b, v4
	v_mul_f32_e32 v5, 0x3fb8aa3b, v5
	v_mul_f32_e32 v6, 0x3fb8aa3b, v6
	v_mul_f32_e32 v7, 0x3fb8aa3b, v7
	v_mul_f32_e32 v8, 0x3fb8aa3b, v8
	v_mul_f32_e32 v9, 0x3fb8aa3b, v9
	v_mul_f32_e32 v10, 0x3fb8aa3b, v10
	v_mul_f32_e32 v11, 0x3fb8aa3b, v11
	v_exp_f32_e32 v4, v4
	v_exp_f32_e32 v5, v5
	v_exp_f32_e32 v6, v6
	v_exp_f32_e32 v7, v7
	v_exp_f32_e32 v8, v8
	v_exp_f32_e32 v9, v9
	v_exp_f32_e32 v10, v10
	v_exp_f32_e32 v11, v11
	v_add_f32_e32 v4, 1.0, v4
	v_add_f32_e32 v5, 1.0, v5
	v_add_f32_e32 v6, 1.0, v6
	v_add_f32_e32 v7, 1.0, v7
	v_add_f32_e32 v8, 1.0, v8
	v_add_f32_e32 v9, 1.0, v9
	v_add_f32_e32 v10, 1.0, v10
	v_add_f32_e32 v11, 1.0, v11
	v_rcp_f32_e32 v4, v4
	v_rcp_f32_e32 v5, v5
	v_rcp_f32_e32 v6, v6
	v_rcp_f32_e32 v7, v7
	v_rcp_f32_e32 v8, v8
	v_rcp_f32_e32 v9, v9
	v_rcp_f32_e32 v10, v10
	v_rcp_f32_e32 v11, v11
	v_pk_fma_f32 v[4:5], v[4:5], 2.0, 1.0 op_sel_hi:[1,0,0] neg_lo:[1,0,0] neg_hi:[1,0,0]
	v_pk_fma_f32 v[6:7], v[6:7], 2.0, 1.0 op_sel_hi:[1,0,0] neg_lo:[1,0,0] neg_hi:[1,0,0]
	v_pk_fma_f32 v[8:9], v[8:9], 2.0, 1.0 op_sel_hi:[1,0,0] neg_lo:[1,0,0] neg_hi:[1,0,0]
	v_pk_fma_f32 v[10:11], v[10:11], 2.0, 1.0 op_sel_hi:[1,0,0] neg_lo:[1,0,0] neg_hi:[1,0,0]
	v_cvt_pk_bf16_f32 v4, v4, v5
	v_cvt_pk_bf16_f32 v5, v6, v7
	v_cvt_pk_bf16_f32 v6, v8, v9
	v_cvt_pk_bf16_f32 v7, v10, v11
	s_waitcnt vmcnt(10)
	v_mov_b64_e32 v[8:9], v[194:195]
	v_mov_b64_e32 v[10:11], v[196:197]
	s_waitcnt vmcnt(9)
	v_mov_b64_e32 v[12:13], v[198:199]
	v_mov_b64_e32 v[14:15], v[200:201]
	v_lshlrev_b32_e32 v16, 16, v12
	v_and_b32_e32 v17, 0xffff0000, v12
	v_lshlrev_b32_e32 v18, 16, v13
	v_and_b32_e32 v19, 0xffff0000, v13
	v_lshlrev_b32_e32 v20, 16, v14
	v_and_b32_e32 v21, 0xffff0000, v14
	v_lshlrev_b32_e32 v22, 16, v15
	v_and_b32_e32 v23, 0xffff0000, v15
	v_add_f32_e32 v12, v16, v16
	v_add_f32_e32 v13, v17, v17
	v_add_f32_e32 v14, v18, v18
	v_add_f32_e32 v15, v19, v19
	v_add_f32_e32 v16, v20, v20
	v_add_f32_e32 v17, v21, v21
	v_add_f32_e32 v18, v22, v22
	v_add_f32_e32 v19, v23, v23
	v_mul_f32_e32 v12, 0x3fb8aa3b, v12
	v_mul_f32_e32 v13, 0x3fb8aa3b, v13
	v_mul_f32_e32 v14, 0x3fb8aa3b, v14
	v_mul_f32_e32 v15, 0x3fb8aa3b, v15
	v_mul_f32_e32 v16, 0x3fb8aa3b, v16
	v_mul_f32_e32 v17, 0x3fb8aa3b, v17
	v_mul_f32_e32 v18, 0x3fb8aa3b, v18
	v_mul_f32_e32 v19, 0x3fb8aa3b, v19
	v_exp_f32_e32 v12, v12
	v_exp_f32_e32 v13, v13
	v_exp_f32_e32 v14, v14
	v_exp_f32_e32 v15, v15
	v_exp_f32_e32 v16, v16
	v_exp_f32_e32 v17, v17
	v_exp_f32_e32 v18, v18
	v_exp_f32_e32 v19, v19
	v_add_f32_e32 v12, 1.0, v12
	v_add_f32_e32 v13, 1.0, v13
	v_add_f32_e32 v14, 1.0, v14
	v_add_f32_e32 v15, 1.0, v15
	v_add_f32_e32 v16, 1.0, v16
	v_add_f32_e32 v17, 1.0, v17
	v_add_f32_e32 v18, 1.0, v18
	v_add_f32_e32 v19, 1.0, v19
	v_rcp_f32_e32 v12, v12
	v_rcp_f32_e32 v13, v13
	v_rcp_f32_e32 v14, v14
	v_rcp_f32_e32 v15, v15
	v_rcp_f32_e32 v16, v16
	v_rcp_f32_e32 v17, v17
	v_rcp_f32_e32 v18, v18
	v_rcp_f32_e32 v19, v19
	v_pk_fma_f32 v[12:13], v[12:13], 2.0, 1.0 op_sel_hi:[1,0,0] neg_lo:[1,0,0] neg_hi:[1,0,0]
	v_pk_fma_f32 v[14:15], v[14:15], 2.0, 1.0 op_sel_hi:[1,0,0] neg_lo:[1,0,0] neg_hi:[1,0,0]
	v_pk_fma_f32 v[16:17], v[16:17], 2.0, 1.0 op_sel_hi:[1,0,0] neg_lo:[1,0,0] neg_hi:[1,0,0]
	v_pk_fma_f32 v[18:19], v[18:19], 2.0, 1.0 op_sel_hi:[1,0,0] neg_lo:[1,0,0] neg_hi:[1,0,0]
	v_cvt_pk_bf16_f32 v12, v12, v13
	v_cvt_pk_bf16_f32 v13, v14, v15
	v_cvt_pk_bf16_f32 v14, v16, v17
	v_cvt_pk_bf16_f32 v15, v18, v19
	s_waitcnt vmcnt(8)
; __device__ __forceinline__ float lo16(unsigned u) { return __uint_as_float(u << 16); }
; __device__ __forceinline__ float hi16(unsigned u) { return __uint_as_float(u & 0xffff0000u); }
; __device__ __forceinline__ unsigned pk2(float lo, float hi) { f32x2n v = {lo, hi}; bf16x2n b = __builtin_convertvector(v, bf16x2n); return __builtin_bit_cast(unsigned, b); }
; __device__ __forceinline__ float sigm(float x) { return __builtin_amdgcn_rcpf(1.f + __expf(-x)); }
; __device__ __forceinline__ float tanh_fast(float x) { float e = __expf(2.f * x); return 1.f - 2.f * __builtin_amdgcn_rcpf(e + 1.f); }
; #define p (kparams())
; template <int MODE>
; __device__ __forceinline__ bf16x8 xf_frag(const bf16_t* p) {
;   const u32x4 u = *(const u32x4*)p;
;   if (MODE == 0) return __builtin_bit_cast(bf16x8, u);
;   float f[8] = {lo16(u.x), hi16(u.x), lo16(u.y), hi16(u.y), lo16(u.z), hi16(u.z), lo16(u.w), hi16(u.w)};
; #pragma unroll
;   for (int e = 0; e < 8; ++e) f[e] = MODE == 1 ? tanh_fast(f[e]) : sigm(f[e]);
;   u32x4 o; o.x = pk2(f[0], f[1]); o.y = pk2(f[2], f[3]); o.z = pk2(f[4], f[5]); o.w = pk2(f[6], f[7]);
;   return __builtin_bit_cast(bf16x8, o);
; __device__ __forceinline__ void rwkv_prep_item(const int wv_, KPR p, int l, int item, bf16_t* tile) {
;     ...
; #pragma unroll
;   for (int d = 0; d < 2; ++d)
; #pragma unroll
;     for (int ks = 0; ks < 2; ++ks) { aw[d][ks] = xf_frag<1>(arow + O_WL + d * 64 + ks * 32 + tq * 8); aa[d][ks] = xf_frag<0>(arow + O_AL + d * 64 + ks * 32 + tq * 8); }
; #pragma unroll
;   for (int ks = 0; ks < 4; ++ks) ag[ks] = xf_frag<2>(arow + O_GL + ks * 32 + tq * 8);
	v_mov_b64_e32 v[16:17], v[202:203]
	v_mov_b64_e32 v[18:19], v[204:205]
	s_waitcnt vmcnt(7)
	v_mov_b64_e32 v[20:21], v[206:207]
	v_mov_b64_e32 v[22:23], v[208:209]
	v_lshlrev_b32_e32 v24, 16, v20
	v_and_b32_e32 v25, 0xffff0000, v20
	v_lshlrev_b32_e32 v26, 16, v21
	v_and_b32_e32 v27, 0xffff0000, v21
	v_lshlrev_b32_e32 v28, 16, v22
	v_and_b32_e32 v29, 0xffff0000, v22
	v_lshlrev_b32_e32 v30, 16, v23
	v_and_b32_e32 v31, 0xffff0000, v23
	v_add_f32_e32 v20, v24, v24
	v_add_f32_e32 v21, v25, v25
	v_add_f32_e32 v22, v26, v26
	v_add_f32_e32 v23, v27, v27
	v_add_f32_e32 v24, v28, v28
	v_add_f32_e32 v25, v29, v29
	v_add_f32_e32 v26, v30, v30
	v_add_f32_e32 v27, v31, v31
	v_mul_f32_e32 v20, 0x3fb8aa3b, v20
	v_mul_f32_e32 v21, 0x3fb8aa3b, v21
	v_mul_f32_e32 v22, 0x3fb8aa3b, v22
	v_mul_f32_e32 v23, 0x3fb8aa3b, v23
	v_mul_f32_e32 v24, 0x3fb8aa3b, v24
	v_mul_f32_e32 v25, 0x3fb8aa3b, v25
	v_mul_f32_e32 v26, 0x3fb8aa3b, v26
	v_mul_f32_e32 v27, 0x3fb8aa3b, v27
	v_exp_f32_e32 v20, v20
	v_exp_f32_e32 v21, v21
	v_exp_f32_e32 v22, v22
	v_exp_f32_e32 v23, v23
	v_exp_f32_e32 v24, v24
	v_exp_f32_e32 v25, v25
	v_exp_f32_e32 v26, v26
	v_exp_f32_e32 v27, v27
	v_add_f32_e32 v20, 1.0, v20
	v_add_f32_e32 v21, 1.0, v21
	v_add_f32_e32 v22, 1.0, v22
	v_add_f32_e32 v23, 1.0, v23
	v_add_f32_e32 v24, 1.0, v24
	v_add_f32_e32 v25, 1.0, v25
	v_add_f32_e32 v26, 1.0, v26
	v_add_f32_e32 v27, 1.0, v27
	v_rcp_f32_e32 v20, v20
	v_rcp_f32_e32 v21, v21
	v_rcp_f32_e32 v22, v22
	v_rcp_f32_e32 v23, v23
	v_rcp_f32_e32 v24, v24
	v_rcp_f32_e32 v25, v25
	v_rcp_f32_e32 v26, v26
	v_rcp_f32_e32 v27, v27
	v_pk_fma_f32 v[20:21], v[20:21], 2.0, 1.0 op_sel_hi:[1,0,0] neg_lo:[1,0,0] neg_hi:[1,0,0]
	v_pk_fma_f32 v[22:23], v[22:23], 2.0, 1.0 op_sel_hi:[1,0,0] neg_lo:[1,0,0] neg_hi:[1,0,0]
	v_pk_fma_f32 v[24:25], v[24:25], 2.0, 1.0 op_sel_hi:[1,0,0] neg_lo:[1,0,0] neg_hi:[1,0,0]
	v_pk_fma_f32 v[26:27], v[26:27], 2.0, 1.0 op_sel_hi:[1,0,0] neg_lo:[1,0,0] neg_hi:[1,0,0]
	v_cvt_pk_bf16_f32 v20, v20, v21
	v_cvt_pk_bf16_f32 v21, v22, v23
	v_cvt_pk_bf16_f32 v22, v24, v25
	v_cvt_pk_bf16_f32 v23, v26, v27
	s_waitcnt vmcnt(6)
	v_mov_b64_e32 v[24:25], v[210:211]
	v_mov_b64_e32 v[26:27], v[212:213]
	s_waitcnt vmcnt(5)
	v_mov_b64_e32 v[28:29], v[214:215]
	v_mov_b64_e32 v[30:31], v[216:217]
	v_lshlrev_b32_e32 v32, 16, v28
	v_and_b32_e32 v33, 0xffff0000, v28
	v_lshlrev_b32_e32 v34, 16, v29
	v_and_b32_e32 v35, 0xffff0000, v29
	v_lshlrev_b32_e32 v36, 16, v30
	v_and_b32_e32 v37, 0xffff0000, v30
	v_lshlrev_b32_e32 v38, 16, v31
	v_and_b32_e32 v39, 0xffff0000, v31
	v_add_f32_e32 v28, v32, v32
	v_add_f32_e32 v29, v33, v33
	v_add_f32_e32 v30, v34, v34
	v_add_f32_e32 v31, v35, v35
	v_add_f32_e32 v32, v36, v36
	v_add_f32_e32 v33, v37, v37
	v_add_f32_e32 v34, v38, v38
	v_add_f32_e32 v35, v39, v39
	v_mul_f32_e32 v28, 0x3fb8aa3b, v28
	v_mul_f32_e32 v29, 0x3fb8aa3b, v29
	v_mul_f32_e32 v30, 0x3fb8aa3b, v30
	v_mul_f32_e32 v31, 0x3fb8aa3b, v31
	v_mul_f32_e32 v32, 0x3fb8aa3b, v32
	v_mul_f32_e32 v33, 0x3fb8aa3b, v33
	v_mul_f32_e32 v34, 0x3fb8aa3b, v34
	v_mul_f32_e32 v35, 0x3fb8aa3b, v35
	v_exp_f32_e32 v28, v28
	v_exp_f32_e32 v29, v29
	v_exp_f32_e32 v30, v30
	v_exp_f32_e32 v31, v31
	v_exp_f32_e32 v32, v32
	v_exp_f32_e32 v33, v33
	v_exp_f32_e32 v34, v34
	v_exp_f32_e32 v35, v35
	v_add_f32_e32 v28, 1.0, v28
	v_add_f32_e32 v29, 1.0, v29
	v_add_f32_e32 v30, 1.0, v30
	v_add_f32_e32 v31, 1.0, v31
	v_add_f32_e32 v32, 1.0, v32
	v_add_f32_e32 v33, 1.0, v33
	v_add_f32_e32 v34, 1.0, v34
	v_add_f32_e32 v35, 1.0, v35
	v_rcp_f32_e32 v28, v28
	v_rcp_f32_e32 v29, v29
	v_rcp_f32_e32 v30, v30
	v_rcp_f32_e32 v31, v31
	v_rcp_f32_e32 v32, v32
	v_rcp_f32_e32 v33, v33
	v_rcp_f32_e32 v34, v34
	v_rcp_f32_e32 v35, v35
	v_pk_fma_f32 v[28:29], v[28:29], 2.0, 1.0 op_sel_hi:[1,0,0] neg_lo:[1,0,0] neg_hi:[1,0,0]
	v_pk_fma_f32 v[30:31], v[30:31], 2.0, 1.0 op_sel_hi:[1,0,0] neg_lo:[1,0,0] neg_hi:[1,0,0]
	v_pk_fma_f32 v[32:33], v[32:33], 2.0, 1.0 op_sel_hi:[1,0,0] neg_lo:[1,0,0] neg_hi:[1,0,0]
	v_pk_fma_f32 v[34:35], v[34:35], 2.0, 1.0 op_sel_hi:[1,0,0] neg_lo:[1,0,0] neg_hi:[1,0,0]
	v_cvt_pk_bf16_f32 v28, v28, v29
	v_cvt_pk_bf16_f32 v29, v30, v31
	v_cvt_pk_bf16_f32 v30, v32, v33
	v_cvt_pk_bf16_f32 v31, v34, v35
	s_waitcnt vmcnt(4)
	v_mov_b64_e32 v[32:33], v[218:219]
	v_mov_b64_e32 v[34:35], v[220:221]
	s_waitcnt vmcnt(3)
	v_mov_b64_e32 v[36:37], v[222:223]
	v_mov_b64_e32 v[38:39], v[224:225]
	v_lshlrev_b32_e32 v40, 16, v36
	v_and_b32_e32 v36, 0xffff0000, v36
	v_lshlrev_b32_e32 v41, 16, v37
	v_and_b32_e32 v37, 0xffff0000, v37
	v_lshlrev_b32_e32 v42, 16, v38
	v_and_b32_e32 v38, 0xffff0000, v38
	v_lshlrev_b32_e32 v43, 16, v39
	v_and_b32_e32 v39, 0xffff0000, v39
	v_mul_f32_e32 v40, 0xbfb8aa3b, v40
	v_mul_f32_e32 v36, 0xbfb8aa3b, v36
	v_mul_f32_e32 v41, 0xbfb8aa3b, v41
	v_mul_f32_e32 v37, 0xbfb8aa3b, v37
	v_mul_f32_e32 v42, 0xbfb8aa3b, v42
	v_mul_f32_e32 v38, 0xbfb8aa3b, v38
	v_mul_f32_e32 v43, 0xbfb8aa3b, v43
	v_mul_f32_e32 v39, 0xbfb8aa3b, v39
	v_exp_f32_e32 v40, v40
	v_exp_f32_e32 v36, v36
	v_exp_f32_e32 v41, v41
	v_exp_f32_e32 v37, v37
	v_exp_f32_e32 v42, v42
	v_exp_f32_e32 v38, v38
	v_exp_f32_e32 v43, v43
	v_exp_f32_e32 v39, v39
	v_add_f32_e32 v40, 1.0, v40
	v_add_f32_e32 v36, 1.0, v36
	v_add_f32_e32 v41, 1.0, v41
	v_add_f32_e32 v37, 1.0, v37
	v_add_f32_e32 v42, 1.0, v42
	v_add_f32_e32 v38, 1.0, v38
	v_add_f32_e32 v43, 1.0, v43
	v_add_f32_e32 v39, 1.0, v39
	v_rcp_f32_e32 v40, v40
	v_rcp_f32_e32 v36, v36
	v_rcp_f32_e32 v41, v41
	v_rcp_f32_e32 v37, v37
	v_rcp_f32_e32 v42, v42
	v_rcp_f32_e32 v38, v38
	v_rcp_f32_e32 v43, v43
	v_rcp_f32_e32 v39, v39
	v_cvt_pk_bf16_f32 v36, v40, v36
	v_cvt_pk_bf16_f32 v37, v41, v37
	v_cvt_pk_bf16_f32 v38, v42, v38
	v_cvt_pk_bf16_f32 v39, v43, v39
	s_waitcnt vmcnt(2)
; __device__ __forceinline__ float lo16(unsigned u) { return __uint_as_float(u << 16); }
; __device__ __forceinline__ float hi16(unsigned u) { return __uint_as_float(u & 0xffff0000u); }
; __device__ __forceinline__ unsigned pk2(float lo, float hi) { f32x2n v = {lo, hi}; bf16x2n b = __builtin_convertvector(v, bf16x2n); return __builtin_bit_cast(unsigned, b); }
; __device__ __forceinline__ float sigm(float x) { return __builtin_amdgcn_rcpf(1.f + __expf(-x)); }
; __device__ __forceinline__ float tanh_fast(float x) { float e = __expf(2.f * x); return 1.f - 2.f * __builtin_amdgcn_rcpf(e + 1.f); }
; #define p (kparams())
; #define ws (kparams()->ws)
; template <int MODE>
; __device__ __forceinline__ bf16x8 xf_frag(const bf16_t* p) {
;   const u32x4 u = *(const u32x4*)p;
;   if (MODE == 0) return __builtin_bit_cast(bf16x8, u);
;   float f[8] = {lo16(u.x), hi16(u.x), lo16(u.y), hi16(u.y), lo16(u.z), hi16(u.z), lo16(u.w), hi16(u.w)};
; #pragma unroll
;   for (int e = 0; e < 8; ++e) f[e] = MODE == 1 ? tanh_fast(f[e]) : sigm(f[e]);
;   u32x4 o; o.x = pk2(f[0], f[1]); o.y = pk2(f[2], f[3]); o.z = pk2(f[4], f[5]); o.w = pk2(f[6], f[7]);
;   return __builtin_bit_cast(bf16x8, o);
; __device__ __forceinline__ void rwkv_prep_item(const int wv_, KPR p, int l, int item, bf16_t* tile) {
;     ...
;     for (int ks = 0; ks < 2; ++ks) { aw[d][ks] = xf_frag<1>(arow + O_WL + d * 64 + ks * 32 + tq * 8); aa[d][ks] = xf_frag<0>(arow + O_AL + d * 64 + ks * 32 + tq * 8); }
; #pragma unroll
;   for (int ks = 0; ks < 4; ++ks) ag[ks] = xf_frag<2>(arow + O_GL + ks * 32 + tq * 8);
;   const bf16_t* W2T = (const bf16_t*)(p->ws + WS_SW); const bf16_t* A2T = W2T + 65536; const bf16_t* G2T = W2T + 131072;
;   bf16_t* PRE = (bf16_t*)(p->ws + R_PRE);
;   const size_t AE = (size_t)T * 512;
;     ...
;     const float kkw = p->in[I_RWKK][l * C + c];
;     const float ka = p->in[I_RWKA][l * C + c];
;     const float w00 = p->in[I_RWW0][(l * 2 + 0) * C + c], w01 = p->in[I_RWW0][(l * 2 + 1) * C + c];
;     const float a00 = p->in[I_RWA0][(l * 2 + 0) * C + c], a01 = p->in[I_RWA0][(l * 2 + 1) * C + c];
	v_mov_b64_e32 v[40:41], v[226:227]
	v_mov_b64_e32 v[42:43], v[228:229]
	v_lshlrev_b32_e32 v44, 16, v40
	v_and_b32_e32 v40, 0xffff0000, v40
	v_lshlrev_b32_e32 v45, 16, v41
	v_and_b32_e32 v41, 0xffff0000, v41
	v_lshlrev_b32_e32 v46, 16, v42
	v_and_b32_e32 v42, 0xffff0000, v42
	v_lshlrev_b32_e32 v47, 16, v43
	v_and_b32_e32 v43, 0xffff0000, v43
	v_mul_f32_e32 v44, 0xbfb8aa3b, v44
	v_mul_f32_e32 v40, 0xbfb8aa3b, v40
	v_mul_f32_e32 v45, 0xbfb8aa3b, v45
	v_mul_f32_e32 v41, 0xbfb8aa3b, v41
	v_mul_f32_e32 v46, 0xbfb8aa3b, v46
	v_mul_f32_e32 v42, 0xbfb8aa3b, v42
	v_mul_f32_e32 v47, 0xbfb8aa3b, v47
	v_mul_f32_e32 v43, 0xbfb8aa3b, v43
	v_exp_f32_e32 v44, v44
	v_exp_f32_e32 v40, v40
	v_exp_f32_e32 v45, v45
	v_exp_f32_e32 v41, v41
	v_exp_f32_e32 v46, v46
	v_exp_f32_e32 v42, v42
	v_exp_f32_e32 v47, v47
	v_exp_f32_e32 v43, v43
	v_add_f32_e32 v44, 1.0, v44
	v_add_f32_e32 v40, 1.0, v40
	v_add_f32_e32 v45, 1.0, v45
	v_add_f32_e32 v41, 1.0, v41
	v_add_f32_e32 v46, 1.0, v46
	v_add_f32_e32 v42, 1.0, v42
	v_add_f32_e32 v47, 1.0, v47
	v_add_f32_e32 v43, 1.0, v43
	v_rcp_f32_e32 v44, v44
	v_rcp_f32_e32 v40, v40
	v_rcp_f32_e32 v45, v45
	v_rcp_f32_e32 v41, v41
	v_rcp_f32_e32 v46, v46
	v_rcp_f32_e32 v42, v42
	v_rcp_f32_e32 v47, v47
	v_rcp_f32_e32 v43, v43
	v_cvt_pk_bf16_f32 v40, v44, v40
	v_cvt_pk_bf16_f32 v41, v45, v41
	v_cvt_pk_bf16_f32 v42, v46, v42
	v_cvt_pk_bf16_f32 v43, v47, v43
	s_waitcnt vmcnt(1)
	v_mov_b64_e32 v[44:45], v[230:231]
	v_mov_b64_e32 v[46:47], v[232:233]
	v_lshlrev_b32_e32 v50, 16, v44
	v_and_b32_e32 v44, 0xffff0000, v44
	v_lshlrev_b32_e32 v51, 16, v45
	v_and_b32_e32 v45, 0xffff0000, v45
	v_mul_f32_e32 v50, 0xbfb8aa3b, v50
	v_mul_f32_e32 v44, 0xbfb8aa3b, v44
	v_mul_f32_e32 v51, 0xbfb8aa3b, v51
	v_mul_f32_e32 v45, 0xbfb8aa3b, v45
	v_exp_f32_e32 v50, v50
	v_exp_f32_e32 v44, v44
	v_exp_f32_e32 v51, v51
	v_exp_f32_e32 v45, v45
	v_add_f32_e32 v50, 1.0, v50
	v_add_f32_e32 v44, 1.0, v44
	v_add_f32_e32 v51, 1.0, v51
	v_add_f32_e32 v45, 1.0, v45
	v_rcp_f32_e32 v50, v50
	v_rcp_f32_e32 v44, v44
	v_rcp_f32_e32 v51, v51
	v_rcp_f32_e32 v45, v45
	v_lshlrev_b32_e32 v62, 16, v46
	v_cvt_pk_bf16_f32 v44, v50, v44
	v_and_b32_e32 v46, 0xffff0000, v46
	v_cvt_pk_bf16_f32 v45, v51, v45
	s_waitcnt vmcnt(0)
	v_mov_b64_e32 v[48:49], v[234:235]
	v_mov_b64_e32 v[50:51], v[236:237]
	v_lshlrev_b32_e32 v63, 16, v47
	v_and_b32_e32 v47, 0xffff0000, v47
	v_mul_f32_e32 v62, 0xbfb8aa3b, v62
	v_mul_f32_e32 v46, 0xbfb8aa3b, v46
	v_mul_f32_e32 v63, 0xbfb8aa3b, v63
	v_mul_f32_e32 v47, 0xbfb8aa3b, v47
	v_exp_f32_e32 v62, v62
	v_exp_f32_e32 v46, v46
	v_exp_f32_e32 v63, v63
	v_exp_f32_e32 v47, v47
	v_add_f32_e32 v62, 1.0, v62
	v_add_f32_e32 v46, 1.0, v46
	v_add_f32_e32 v63, 1.0, v63
	v_add_f32_e32 v47, 1.0, v47
	v_rcp_f32_e32 v62, v62
	v_rcp_f32_e32 v46, v46
	v_rcp_f32_e32 v63, v63
	v_rcp_f32_e32 v47, v47
	v_cvt_pk_bf16_f32 v46, v62, v46
	v_cvt_pk_bf16_f32 v47, v63, v47
	v_lshlrev_b32_e32 v62, 16, v48
	v_and_b32_e32 v48, 0xffff0000, v48
	v_lshlrev_b32_e32 v63, 16, v49
	v_and_b32_e32 v49, 0xffff0000, v49
	v_mul_f32_e32 v62, 0xbfb8aa3b, v62
	v_mul_f32_e32 v48, 0xbfb8aa3b, v48
	v_mul_f32_e32 v63, 0xbfb8aa3b, v63
	v_mul_f32_e32 v49, 0xbfb8aa3b, v49
	v_exp_f32_e32 v62, v62
	v_exp_f32_e32 v48, v48
	v_exp_f32_e32 v63, v63
	v_exp_f32_e32 v49, v49
	v_add_f32_e32 v62, 1.0, v62
	v_add_f32_e32 v48, 1.0, v48
	v_add_f32_e32 v63, 1.0, v63
	v_add_f32_e32 v49, 1.0, v49
	v_rcp_f32_e32 v62, v62
	v_rcp_f32_e32 v48, v48
	v_rcp_f32_e32 v63, v63
	v_rcp_f32_e32 v49, v49
	v_lshlrev_b32_e32 v64, 16, v50
	v_and_b32_e32 v50, 0xffff0000, v50
	v_lshlrev_b32_e32 v65, 16, v51
	v_and_b32_e32 v51, 0xffff0000, v51
	v_mul_f32_e32 v64, 0xbfb8aa3b, v64
	v_mul_f32_e32 v50, 0xbfb8aa3b, v50
	v_mul_f32_e32 v65, 0xbfb8aa3b, v65
	v_mul_f32_e32 v51, 0xbfb8aa3b, v51
	v_exp_f32_e32 v64, v64
	v_exp_f32_e32 v50, v50
	v_exp_f32_e32 v65, v65
	v_exp_f32_e32 v51, v51
	v_cvt_pk_bf16_f32 v48, v62, v48
	v_cvt_pk_bf16_f32 v49, v63, v49
	v_lshl_add_u64 v[62:63], s[14:15], 0, v[0:1]
	s_mov_b64 s[14:15], 0x1080000
	v_lshl_add_u64 v[0:1], v[62:63], 0, s[14:15]
	s_mov_b64 s[14:15], 0x10a0000
	v_lshl_add_u64 v[72:73], v[62:63], 0, s[14:15]
	s_mov_b64 s[14:15], 0x10c0000
	v_add_f32_e32 v64, 1.0, v64
	v_add_f32_e32 v50, 1.0, v50
	v_add_f32_e32 v65, 1.0, v65
	v_add_f32_e32 v51, 1.0, v51
	v_lshl_add_u64 v[74:75], v[62:63], 0, s[14:15]
	s_load_dwordx2 s[14:15], s[12:13], 0x58
	s_load_dwordx2 s[18:19], s[12:13], 0x68
	s_nop 0
	s_load_dwordx2 s[12:13], s[12:13], 0x88
	v_rcp_f32_e32 v64, v64
	v_rcp_f32_e32 v50, v50
	v_rcp_f32_e32 v65, v65
	v_rcp_f32_e32 v51, v51
	v_cvt_pk_bf16_f32 v50, v64, v50
	v_cvt_pk_bf16_f32 v51, v65, v51
; __device__ __forceinline__ float bf2f(bf16_t h) { return __uint_as_float((unsigned)h << 16); }
; __device__ __forceinline__ void conv4(const bf16_t* tile, const float* cw, int ch, int tq, float (&o)[4]) {
;   const float w0 = cw[ch], w1 = cw[1536 + ch], w2 = cw[3072 + ch];
;   float xs[6];
; #pragma unroll
;   for (int i = 0; i < 6; ++i) xs[i] = bf2f(tile[(tq * 4 + i) * RPS + ch]);
; #pragma unroll
;   for (int j = 0; j < 4; ++j) o[j] = w0 * xs[j] + w1 * xs[j + 1] + w2 * xs[j + 2];
; }
; __device__ __forceinline__ void rwkv_prep_item(const int wv_, KPR p, int l, int item, bf16_t* tile) {
;     ...
;   for (int nt = 0; nt < 4; ++nt) { const int c = wid * 64 + nt * 16 + cl;
;     f32x4 accw[2], acca[2], accg = (f32x4){0.f, 0.f, 0.f, 0.f};
; #pragma unroll
;     for (int d = 0; d < 2; ++d) { accw[d] = (f32x4){0.f, 0.f, 0.f, 0.f}; acca[d] = (f32x4){0.f, 0.f, 0.f, 0.f};
; #pragma unroll
;       for (int ks = 0; ks < 2; ++ks) {
;         accw[d] = __builtin_amdgcn_mfma_f32_16x16x32_bf16(aw[d][ks], ld_frag(W2T + ((size_t)d * C + c) * 64 + ks * 32 + tq * 8), accw[d], 0, 0, 0);
;         acca[d] = __builtin_amdgcn_mfma_f32_16x16x32_bf16(aa[d][ks], ld_frag(A2T + ((size_t)d * C + c) * 64 + ks * 32 + tq * 8), acca[d], 0, 0, 0); } }
; #pragma unroll
;     for (int ks = 0; ks < 4; ++ks) accg = __builtin_amdgcn_mfma_f32_16x16x32_bf16(ag[ks], ld_frag(G2T + (size_t)c * 128 + ks * 32 + tq * 8), accg, 0, 0, 0);
;     float r4[4], k4[4], v4[4]; conv4(tile, cw, c, tq, r4); conv4(tile, cw, 512 + c, tq, k4); conv4(tile, cw, 1024 + c, tq, v4);
.LBB0_435:
	v_ashrrev_i32_e32 v85, 31, v84
	v_lshlrev_b64 v[52:53], 7, v[84:85]
	v_lshl_add_u64 v[90:91], v[0:1], 0, v[52:53]
	v_lshl_add_u64 v[92:93], v[72:73], 0, v[52:53]
	v_lshl_add_u64 v[238:239], v[90:91], 0, s[92:93]
	v_lshl_add_u64 v[240:241], v[92:93], 0, s[92:93]
	v_lshlrev_b64 v[52:53], 8, v[84:85]
	v_lshl_add_u64 v[124:125], v[74:75], 0, v[52:53]
	global_load_dwordx4 v[190:193], v[90:91], off
	global_load_dwordx4 v[194:197], v[90:91], off offset:64
	global_load_dwordx4 v[198:201], v[92:93], off
	global_load_dwordx4 v[202:205], v[92:93], off offset:64
	global_load_dwordx4 v[206:209], v[238:239], off
	global_load_dwordx4 v[210:213], v[238:239], off offset:64
	global_load_dwordx4 v[214:217], v[240:241], off
	global_load_dwordx4 v[218:221], v[240:241], off offset:64
	global_load_dwordx4 v[222:225], v[124:125], off
	global_load_dwordx4 v[226:229], v[124:125], off offset:64
	global_load_dwordx4 v[230:233], v[124:125], off offset:128
	global_load_dwordx4 v[234:237], v[124:125], off offset:192
	v_add_u32_e32 v106, s20, v3
	s_add_i32 s20, s20, 32
	s_cmpk_lg_i32 s20, 0x80
	s_waitcnt vmcnt(11)
	v_mfma_f32_16x16x32_bf16 v[68:71], v[4:7], v[190:193], 0
	s_waitcnt vmcnt(10)
	v_mfma_f32_16x16x32_bf16 v[68:71], v[12:15], v[194:197], v[68:71]
	s_waitcnt vmcnt(9)
	v_mfma_f32_16x16x32_bf16 v[64:67], v[8:11], v[198:201], 0
	s_waitcnt vmcnt(8)
	v_mfma_f32_16x16x32_bf16 v[64:67], v[16:19], v[202:205], v[64:67]
	s_waitcnt vmcnt(7)
	v_mfma_f32_16x16x32_bf16 v[60:63], v[20:23], v[206:209], 0
	s_waitcnt vmcnt(6)
	v_mfma_f32_16x16x32_bf16 v[60:63], v[28:31], v[210:213], v[60:63]
	s_waitcnt vmcnt(5)
	v_mfma_f32_16x16x32_bf16 v[56:59], v[24:27], v[214:217], 0
	s_waitcnt vmcnt(4)
	v_mfma_f32_16x16x32_bf16 v[56:59], v[32:35], v[218:221], v[56:59]
	s_waitcnt vmcnt(3)
	v_mfma_f32_16x16x32_bf16 v[52:55], v[36:39], v[222:225], 0
	s_waitcnt vmcnt(2)
	v_mfma_f32_16x16x32_bf16 v[52:55], v[40:43], v[226:229], v[52:55]
	s_waitcnt vmcnt(1)
	v_mfma_f32_16x16x32_bf16 v[52:55], v[44:47], v[230:233], v[52:55]
	v_lshl_add_u64 v[94:95], v[84:85], 2, s[4:5]
	v_add_co_u32_e32 v96, vcc, s52, v94
	s_waitcnt vmcnt(0)
	v_mfma_f32_16x16x32_bf16 v[52:55], v[48:51], v[234:237], v[52:55]
	v_addc_co_u32_e32 v97, vcc, 0, v95, vcc
	global_load_dword v93, v[96:97], off offset:2048
	global_load_dword v91, v[94:95], off
	ds_read_u16 v92, v106
	v_add_co_u32_e32 v100, vcc, s54, v94
	s_nop 2
	v_cvt_f16_f32_e32 v52, v52
	v_addc_co_u32_e32 v101, vcc, 0, v95, vcc
	s_waitcnt lgkmcnt(0)
	v_lshlrev_b32_e32 v99, 16, v92
	ds_read_u16 v92, v106 offset:3104
	v_add_co_u32_e32 v102, vcc, s80, v94
	v_cvt_f16_f32_e32 v54, v54
	s_nop 0
	v_addc_co_u32_e32 v103, vcc, 0, v95, vcc
	s_waitcnt lgkmcnt(0)
	v_lshlrev_b32_e32 v104, 16, v92
	ds_read_u16 v92, v106 offset:6208
	global_load_dword v90, v[102:103], off offset:-4096
	global_load_dword v111, v[94:95], off offset:2048
	s_waitcnt lgkmcnt(0)
	v_lshlrev_b32_e32 v107, 16, v92
	ds_read_u16 v92, v106 offset:9312
	s_waitcnt lgkmcnt(0)
	v_lshlrev_b32_e32 v108, 16, v92
	ds_read_u16 v92, v106 offset:12416
	s_waitcnt lgkmcnt(0)
	v_lshlrev_b32_e32 v98, 16, v92
	ds_read_u16 v92, v106 offset:15520
	s_waitcnt lgkmcnt(0)
	v_lshlrev_b32_e32 v92, 16, v92
	s_waitcnt vmcnt(3)
	v_mul_f32_e32 v110, v93, v107
	v_mul_f32_e32 v109, v93, v104
	s_waitcnt vmcnt(2)
	v_fmac_f32_e32 v110, v91, v104
	v_add_co_u32_e32 v104, vcc, s63, v94
	v_fmac_f32_e32 v109, v91, v99
	v_mul_f32_e32 v99, v93, v108
	v_mul_f32_e32 v93, v93, v98
	v_addc_co_u32_e32 v105, vcc, 0, v95, vcc
	v_fmac_f32_e32 v99, v91, v107
	v_fmac_f32_e32 v93, v91, v108
	global_load_dword v91, v[104:105], off
	global_load_dword v94, v[100:101], off offset:2048
	ds_read_u16 v95, v106 offset:1024
	ds_read_u16 v100, v106 offset:4128
	s_waitcnt vmcnt(3)
	v_fma_mixlo_f16 v107, v90, v107, v109
	s_waitcnt lgkmcnt(1)
	v_lshlrev_b32_e32 v95, 16, v95
	s_waitcnt lgkmcnt(0)
	v_lshlrev_b32_e32 v101, 16, v100
	ds_read_u16 v100, v106 offset:7232
	s_waitcnt lgkmcnt(0)
	v_lshlrev_b32_e32 v112, 16, v100
	ds_read_u16 v100, v106 offset:10336
	s_waitcnt lgkmcnt(0)
	v_lshlrev_b32_e32 v113, 16, v100
	ds_read_u16 v100, v106 offset:13440
	s_waitcnt lgkmcnt(0)
	v_lshlrev_b32_e32 v114, 16, v100
	ds_read_u16 v100, v106 offset:16544
	s_waitcnt lgkmcnt(0)
	v_lshlrev_b32_e32 v115, 16, v100
	s_waitcnt vmcnt(1)
	v_mul_f32_e32 v116, v91, v101
	v_fmac_f32_e32 v116, v111, v95
	v_mul_f32_e32 v100, v91, v112
	v_mul_f32_e32 v95, v91, v113
	v_mul_f32_e32 v91, v91, v114
	v_fmac_f32_e32 v100, v111, v101
	v_fmac_f32_e32 v95, v111, v112
	v_fmac_f32_e32 v91, v111, v113
	s_waitcnt vmcnt(0)
	v_fmac_f32_e32 v116, v94, v112
	v_fmac_f32_e32 v100, v94, v113
	v_fmac_f32_e32 v95, v94, v114
	v_fmac_f32_e32 v91, v94, v115
	global_load_dword v111, v[96:97], off
	s_nop 0
	global_load_dword v97, v[104:105], off offset:2048
	global_load_dword v94, v[102:103], off
	ds_read_u16 v96, v106 offset:2048
	s_waitcnt lgkmcnt(0)
	v_lshlrev_b32_e32 v102, 16, v96
	ds_read_u16 v96, v106 offset:5152
	s_waitcnt lgkmcnt(0)
	v_lshlrev_b32_e32 v103, 16, v96
	ds_read_u16 v96, v106 offset:8256
	s_waitcnt lgkmcnt(0)
	v_lshlrev_b32_e32 v112, 16, v96
	ds_read_u16 v96, v106 offset:11360
	s_waitcnt lgkmcnt(0)
	v_lshlrev_b32_e32 v113, 16, v96
	ds_read_u16 v96, v106 offset:14464
	s_waitcnt lgkmcnt(0)
	v_lshlrev_b32_e32 v101, 16, v96
	ds_read_u16 v96, v106 offset:17568
	s_waitcnt lgkmcnt(0)
	v_lshlrev_b32_e32 v96, 16, v96
	s_waitcnt vmcnt(1)
; __device__ __forceinline__ float sigm(float x) { return __builtin_amdgcn_rcpf(1.f + __expf(-x)); }
; #define p (kparams())
; __device__ __forceinline__ void rwkv_prep_item(const int wv_, KPR p, int l, int item, bf16_t* tile) {
;     ...
;     float r4[4], k4[4], v4[4]; conv4(tile, cw, c, tq, r4); conv4(tile, cw, 512 + c, tq, k4); conv4(tile, cw, 1024 + c, tq, v4);
;     const float kkw = p->in[I_RWKK][l * C + c];
;     const float ka = p->in[I_RWKA][l * C + c];
;     const float w00 = p->in[I_RWW0][(l * 2 + 0) * C + c], w01 = p->in[I_RWW0][(l * 2 + 1) * C + c];
;     const float a00 = p->in[I_RWA0][(l * 2 + 0) * C + c], a01 = p->in[I_RWA0][(l * 2 + 1) * C + c];
; #pragma unroll
;     for (int j = 0; j < 4; ++j) { const size_t o = (size_t)(R0 + tq * 4 + j) * 512 + c;
;       const float kn = k4[j] * kkw * inv[j];
;       PRE[0 * AE + o] = f2h(r4[j]); PRE[1 * AE + o] = f2h(v4[j]); PRE[2 * AE + o] = f2h(kn);
; #pragma unroll
;       for (int d = 0; d < 2; ++d) { const float wpre = (d == 0 ? w00 : w01) + accw[d][j];
;         const float u = 1.f - __expf(-0.6065306597f * sigm(wpre));
;         const float a = sigm((d == 0 ? a00 : a01) + acca[d][j]);
;         PRE[(3 + d) * AE + o] = f2h(u); PRE[(5 + d) * AE + o] = f2h(kn * a); PRE[(7 + d) * AE + o] = f2h(k4[j] * (1.f + (a - 1.f) * ka)); }
;       PRE[9 * AE + o] = f2h(accg[j]); } }
	v_mul_f32_e32 v106, v97, v103
	v_fmac_f32_e32 v106, v111, v102
	v_mul_f32_e32 v114, v97, v112
	v_add_u32_e32 v102, s78, v84
	v_fmac_f32_e32 v114, v111, v103
	v_ashrrev_i32_e32 v103, 31, v102
	v_lshlrev_b64 v[102:103], 2, v[102:103]
	v_lshl_add_u64 v[104:105], s[10:11], 0, v[102:103]
	v_lshl_add_u64 v[102:103], s[12:13], 0, v[102:103]
	global_load_dword v117, v[102:103], off
	v_add_u32_e32 v102, s22, v84
	v_ashrrev_i32_e32 v103, 31, v102
	v_mul_f32_e32 v115, v97, v113
	v_mul_f32_e32 v97, v97, v101
	v_lshlrev_b64 v[102:103], 2, v[102:103]
	v_fmac_f32_e32 v115, v111, v112
	v_fmac_f32_e32 v97, v111, v113
	global_load_dword v111, v[104:105], off
	v_lshl_add_u64 v[104:105], s[14:15], 0, v[102:103]
	global_load_dword v118, v[104:105], off
	global_load_dword v119, v[104:105], off offset:2048
	v_lshl_add_u64 v[102:103], s[18:19], 0, v[102:103]
	global_load_dword v120, v[102:103], off
	global_load_dword v121, v[102:103], off offset:2048
	v_lshl_add_u64 v[102:103], v[84:85], 1, s[16:17]
	v_lshl_add_u64 v[104:105], v[102:103], 0, v[76:77]
	s_waitcnt vmcnt(6)
	v_fma_mixlo_f16 v109, v94, v112, v106
	v_add_co_u32_e32 v106, vcc, s55, v104
	global_store_short v[104:105], v107, off
	s_nop 0
	v_addc_co_u32_e32 v107, vcc, 0, v105, vcc
	global_store_short v[106:107], v109, off
	v_add_co_u32_e32 v106, vcc, s48, v104
	v_add_u32_e32 v84, 16, v84
	s_nop 0
	v_addc_co_u32_e32 v107, vcc, 0, v105, vcc
	s_waitcnt vmcnt(6)
	v_mul_f32_e32 v85, v116, v111
	s_waitcnt vmcnt(5)
	v_add_f32_e32 v68, v68, v118
	v_mul_f32_e32 v68, 0xbfb8aa3b, v68
	v_exp_f32_e32 v68, v68
	s_waitcnt vmcnt(4)
	v_add_f32_e32 v60, v60, v119
	v_mul_f32_e32 v60, 0xbfb8aa3b, v60
	v_exp_f32_e32 v60, v60
	v_add_f32_e32 v68, 1.0, v68
	v_rcp_f32_e32 v68, v68
	s_waitcnt vmcnt(3)
	v_add_f32_e32 v64, v64, v120
	v_add_f32_e32 v60, 1.0, v60
	v_mul_f32_e32 v64, 0xbfb8aa3b, v64
	v_mul_f32_e32 v68, 0xbf1b4598, v68
	v_mul_f32_e32 v68, 0x3fb8aa3b, v68
	v_exp_f32_e32 v68, v68
	v_rcp_f32_e32 v60, v60
	v_exp_f32_e32 v64, v64
	s_waitcnt vmcnt(2)
	v_add_f32_e32 v56, v56, v121
	v_sub_f32_e32 v68, 1.0, v68
	v_mul_f32_e32 v60, 0xbf1b4598, v60
	v_add_f32_e32 v64, 1.0, v64
	v_cvt_f16_f32_e32 v68, v68
	v_mul_f32_e32 v60, 0x3fb8aa3b, v60
	v_mul_f32_e32 v122, v89, v85
	v_fma_mixlo_f16 v85, v89, v85, 0
	v_rcp_f32_e32 v64, v64
	v_exp_f32_e32 v60, v60
	v_mul_f32_e32 v56, 0xbfb8aa3b, v56
	global_store_short v[106:107], v85, off
	v_add_co_u32_e32 v106, vcc, s49, v104
	v_exp_f32_e32 v56, v56
	s_nop 0
	v_addc_co_u32_e32 v107, vcc, 0, v105, vcc
	global_store_short v[106:107], v68, off
	v_add_co_u32_e32 v106, vcc, s60, v104
	v_fma_mixlo_f16 v68, v122, v64, 0
	s_nop 0
	v_addc_co_u32_e32 v107, vcc, 0, v105, vcc
	v_add_f32_e32 v64, -1.0, v64
	v_sub_f32_e32 v60, 1.0, v60
	global_store_short v[106:107], v68, off
	v_fma_f32 v64, v117, v64, 1.0
	v_add_co_u32_e32 v106, vcc, s61, v104
	v_add_f32_e32 v56, 1.0, v56
	v_cvt_f16_f32_e32 v60, v60
	v_fma_mixlo_f16 v64, v116, v64, 0
	v_addc_co_u32_e32 v107, vcc, 0, v105, vcc
	v_rcp_f32_e32 v56, v56
	global_store_short v[106:107], v64, off
	v_add_co_u32_e32 v106, vcc, s3, v104
	s_nop 1
	v_addc_co_u32_e32 v107, vcc, 0, v105, vcc
	global_store_short v[106:107], v60, off
	v_add_co_u32_e32 v106, vcc, s74, v104
	v_fma_mixlo_f16 v60, v122, v56, 0
	s_nop 0
	v_addc_co_u32_e32 v107, vcc, 0, v105, vcc
	global_store_short v[106:107], v60, off
	v_add_co_u32_e32 v106, vcc, s65, v104
	v_add_f32_e32 v56, -1.0, v56
	s_nop 0
	v_addc_co_u32_e32 v107, vcc, 0, v105, vcc
	v_add_co_u32_e32 v104, vcc, s62, v104
	v_fma_f32 v56, v117, v56, 1.0
	s_nop 0
	v_addc_co_u32_e32 v105, vcc, 0, v105, vcc
	v_fma_mixlo_f16 v56, v116, v56, 0
	global_store_short v[104:105], v52, off
	v_lshl_add_u64 v[104:105], v[102:103], 0, v[78:79]
	global_store_short v[106:107], v56, off
	v_fma_mixlo_f16 v56, v90, v108, v110
	v_add_co_u32_e32 v106, vcc, s55, v104
	global_store_short v[104:105], v56, off
	v_fma_mixlo_f16 v56, v94, v113, v114
	v_addc_co_u32_e32 v107, vcc, 0, v105, vcc
	v_mul_f32_e32 v52, v100, v111
	global_store_short v[106:107], v56, off
	v_add_co_u32_e32 v106, vcc, s48, v104
	v_mul_f32_e32 v60, v88, v52
	v_fma_mixlo_f16 v52, v88, v52, 0
	v_addc_co_u32_e32 v107, vcc, 0, v105, vcc
	global_store_short v[106:107], v52, off
	v_add_f32_e32 v52, v69, v118
	v_mul_f32_e32 v52, 0xbfb8aa3b, v52
	v_exp_f32_e32 v52, v52
	v_add_f32_e32 v56, v65, v120
	v_mul_f32_e32 v56, 0xbfb8aa3b, v56
	v_exp_f32_e32 v56, v56
	v_add_f32_e32 v52, 1.0, v52
	v_rcp_f32_e32 v52, v52
	v_add_co_u32_e32 v64, vcc, s49, v104
	v_add_f32_e32 v56, 1.0, v56
	v_mul_f32_e32 v52, 0xbf1b4598, v52
	v_mul_f32_e32 v52, 0x3fb8aa3b, v52
	v_exp_f32_e32 v52, v52
	v_rcp_f32_e32 v56, v56
	v_addc_co_u32_e32 v65, vcc, 0, v105, vcc
	v_sub_f32_e32 v52, 1.0, v52
	v_cvt_f16_f32_e32 v52, v52
	global_store_short v[64:65], v52, off
	v_add_co_u32_e32 v64, vcc, s60, v104
	v_fma_mixlo_f16 v52, v60, v56, 0
	s_nop 0
	v_addc_co_u32_e32 v65, vcc, 0, v105, vcc
	global_store_short v[64:65], v52, off
	v_add_f32_e32 v52, -1.0, v56
	v_fma_f32 v52, v117, v52, 1.0
	v_add_co_u32_e32 v64, vcc, s61, v104
	v_fma_mixlo_f16 v52, v100, v52, 0
	s_nop 0
	v_addc_co_u32_e32 v65, vcc, 0, v105, vcc
	global_store_short v[64:65], v52, off
	v_add_f32_e32 v52, v61, v119
	v_mul_f32_e32 v52, 0xbfb8aa3b, v52
	v_exp_f32_e32 v52, v52
	v_add_f32_e32 v56, v57, v121
	v_mul_f32_e32 v56, 0xbfb8aa3b, v56
	v_exp_f32_e32 v56, v56
	v_add_f32_e32 v52, 1.0, v52
	v_rcp_f32_e32 v52, v52
	v_fma_mixlo_f16 v64, v94, v101, v115
	v_add_f32_e32 v56, 1.0, v56
	v_rcp_f32_e32 v61, v56
	v_mul_f32_e32 v52, 0xbf1b4598, v52
	v_mul_f32_e32 v52, 0x3fb8aa3b, v52
	v_exp_f32_e32 v52, v52
	v_add_co_u32_e32 v56, vcc, s3, v104
	v_sub_f32_e32 v52, 1.0, v52
; __device__ __forceinline__ float sigm(float x) { return __builtin_amdgcn_rcpf(1.f + __expf(-x)); }
; __device__ __forceinline__ void rwkv_prep_item(const int wv_, KPR p, int l, int item, bf16_t* tile) {
;     ...
; #pragma unroll
;     for (int j = 0; j < 4; ++j) { const size_t o = (size_t)(R0 + tq * 4 + j) * 512 + c;
;       const float kn = k4[j] * kkw * inv[j];
;       PRE[0 * AE + o] = f2h(r4[j]); PRE[1 * AE + o] = f2h(v4[j]); PRE[2 * AE + o] = f2h(kn);
; #pragma unroll
;       for (int d = 0; d < 2; ++d) { const float wpre = (d == 0 ? w00 : w01) + accw[d][j];
;         const float u = 1.f - __expf(-0.6065306597f * sigm(wpre));
;         const float a = sigm((d == 0 ? a00 : a01) + acca[d][j]);
;         PRE[(3 + d) * AE + o] = f2h(u); PRE[(5 + d) * AE + o] = f2h(kn * a); PRE[(7 + d) * AE + o] = f2h(k4[j] * (1.f + (a - 1.f) * ka)); }
;       PRE[9 * AE + o] = f2h(accg[j]); } }
	v_cvt_f16_f32_e32 v52, v52
	v_addc_co_u32_e32 v57, vcc, 0, v105, vcc
	global_store_short v[56:57], v52, off
	v_add_co_u32_e32 v56, vcc, s74, v104
	v_fma_mixlo_f16 v52, v60, v61, 0
	s_nop 0
	v_addc_co_u32_e32 v57, vcc, 0, v105, vcc
	global_store_short v[56:57], v52, off
	v_add_f32_e32 v52, -1.0, v61
	v_fma_f32 v52, v117, v52, 1.0
	v_add_co_u32_e32 v56, vcc, s65, v104
	v_fma_mixlo_f16 v52, v100, v52, 0
	s_nop 0
	v_addc_co_u32_e32 v57, vcc, 0, v105, vcc
	global_store_short v[56:57], v52, off
	v_cvt_f16_f32_e32 v56, v53
	v_add_co_u32_e32 v52, vcc, s62, v104
	v_mul_f32_e32 v60, v95, v111
	s_nop 0
	v_addc_co_u32_e32 v53, vcc, 0, v105, vcc
	global_store_short v[52:53], v56, off
	v_fma_mixlo_f16 v56, v90, v98, v99
	v_lshl_add_u64 v[52:53], v[102:103], 0, v[80:81]
	global_store_short v[52:53], v56, off
	v_add_co_u32_e32 v56, vcc, s55, v52
	v_mul_f32_e32 v61, v87, v60
	s_nop 0
	v_addc_co_u32_e32 v57, vcc, 0, v53, vcc
	global_store_short v[56:57], v64, off
	v_add_co_u32_e32 v56, vcc, s48, v52
	v_fma_mixlo_f16 v60, v87, v60, 0
	s_nop 0
	v_addc_co_u32_e32 v57, vcc, 0, v53, vcc
	global_store_short v[56:57], v60, off
	v_add_f32_e32 v56, v70, v118
	v_mul_f32_e32 v56, 0xbfb8aa3b, v56
	v_exp_f32_e32 v56, v56
	v_add_f32_e32 v57, v66, v120
	v_mul_f32_e32 v57, 0xbfb8aa3b, v57
	v_exp_f32_e32 v57, v57
	v_add_f32_e32 v56, 1.0, v56
	v_rcp_f32_e32 v56, v56
	v_add_f32_e32 v57, 1.0, v57
	v_rcp_f32_e32 v60, v57
	v_mul_f32_e32 v56, 0xbf1b4598, v56
	v_mul_f32_e32 v56, 0x3fb8aa3b, v56
	v_exp_f32_e32 v56, v56
	s_nop 0
	v_sub_f32_e32 v56, 1.0, v56
	v_cvt_f16_f32_e32 v64, v56
	v_add_co_u32_e32 v56, vcc, s49, v52
	s_nop 1
	v_addc_co_u32_e32 v57, vcc, 0, v53, vcc
	global_store_short v[56:57], v64, off
	v_add_co_u32_e32 v56, vcc, s60, v52
	v_fma_mixlo_f16 v64, v61, v60, 0
	s_nop 0
	v_addc_co_u32_e32 v57, vcc, 0, v53, vcc
	global_store_short v[56:57], v64, off
	v_add_f32_e32 v56, -1.0, v60
	v_fma_f32 v56, v117, v56, 1.0
	v_fma_mixlo_f16 v60, v95, v56, 0
	v_add_co_u32_e32 v56, vcc, s61, v52
	s_nop 1
	v_addc_co_u32_e32 v57, vcc, 0, v53, vcc
	global_store_short v[56:57], v60, off
	v_add_f32_e32 v56, v62, v119
	v_mul_f32_e32 v56, 0xbfb8aa3b, v56
	v_exp_f32_e32 v56, v56
	v_add_f32_e32 v57, v58, v121
	v_mul_f32_e32 v57, 0xbfb8aa3b, v57
	v_exp_f32_e32 v57, v57
	v_add_f32_e32 v56, 1.0, v56
	v_rcp_f32_e32 v56, v56
	v_add_f32_e32 v57, 1.0, v57
	v_rcp_f32_e32 v58, v57
	v_mul_f32_e32 v56, 0xbf1b4598, v56
	v_mul_f32_e32 v56, 0x3fb8aa3b, v56
	v_exp_f32_e32 v56, v56
	s_nop 0
	v_sub_f32_e32 v56, 1.0, v56
	v_cvt_f16_f32_e32 v60, v56
	v_add_co_u32_e32 v56, vcc, s3, v52
	s_nop 1
	v_addc_co_u32_e32 v57, vcc, 0, v53, vcc
	global_store_short v[56:57], v60, off
	v_add_co_u32_e32 v56, vcc, s74, v52
	v_fma_mixlo_f16 v60, v61, v58, 0
	s_nop 0
	v_addc_co_u32_e32 v57, vcc, 0, v53, vcc
	global_store_short v[56:57], v60, off
	v_add_f32_e32 v56, -1.0, v58
	v_fma_f32 v56, v117, v56, 1.0
	v_fma_mixlo_f16 v58, v95, v56, 0
	v_add_co_u32_e32 v56, vcc, s65, v52
	v_fma_mixlo_f16 v60, v94, v96, v97
	s_nop 0
	v_addc_co_u32_e32 v57, vcc, 0, v53, vcc
	v_add_co_u32_e32 v52, vcc, s62, v52
	global_store_short v[56:57], v58, off
	s_nop 0
	v_addc_co_u32_e32 v53, vcc, 0, v53, vcc
	global_store_short v[52:53], v54, off
	v_fma_mixlo_f16 v56, v90, v92, v93
	v_lshl_add_u64 v[52:53], v[102:103], 0, v[82:83]
	global_store_short v[52:53], v56, off
	v_add_co_u32_e32 v56, vcc, s55, v52
	v_mul_f32_e32 v54, v91, v111
	s_nop 0
	v_addc_co_u32_e32 v57, vcc, 0, v53, vcc
	global_store_short v[56:57], v60, off
	v_add_co_u32_e32 v56, vcc, s48, v52
	v_mul_f32_e32 v58, v86, v54
	v_fma_mixlo_f16 v54, v86, v54, 0
	v_addc_co_u32_e32 v57, vcc, 0, v53, vcc
	global_store_short v[56:57], v54, off
	v_add_f32_e32 v54, v71, v118
	v_mul_f32_e32 v54, 0xbfb8aa3b, v54
	v_exp_f32_e32 v54, v54
	v_add_f32_e32 v56, v67, v120
	v_mul_f32_e32 v56, 0xbfb8aa3b, v56
	v_exp_f32_e32 v56, v56
	v_add_f32_e32 v54, 1.0, v54
	v_rcp_f32_e32 v54, v54
	v_add_f32_e32 v56, 1.0, v56
	v_rcp_f32_e32 v60, v56
	v_mul_f32_e32 v54, 0xbf1b4598, v54
	v_mul_f32_e32 v54, 0x3fb8aa3b, v54
	v_exp_f32_e32 v54, v54
	v_add_co_u32_e32 v56, vcc, s49, v52
	v_sub_f32_e32 v54, 1.0, v54
	v_cvt_f16_f32_e32 v54, v54
	v_addc_co_u32_e32 v57, vcc, 0, v53, vcc
	global_store_short v[56:57], v54, off
	v_add_co_u32_e32 v56, vcc, s60, v52
	v_fma_mixlo_f16 v54, v58, v60, 0
	s_nop 0
	v_addc_co_u32_e32 v57, vcc, 0, v53, vcc
	global_store_short v[56:57], v54, off
	v_add_f32_e32 v54, -1.0, v60
	v_fma_f32 v54, v117, v54, 1.0
	v_add_co_u32_e32 v56, vcc, s61, v52
	v_fma_mixlo_f16 v54, v91, v54, 0
	s_nop 0
	v_addc_co_u32_e32 v57, vcc, 0, v53, vcc
	global_store_short v[56:57], v54, off
	v_add_f32_e32 v54, v63, v119
	v_mul_f32_e32 v54, 0xbfb8aa3b, v54
	v_exp_f32_e32 v54, v54
	v_add_f32_e32 v56, v59, v121
	v_mul_f32_e32 v56, 0xbfb8aa3b, v56
	v_exp_f32_e32 v56, v56
	v_add_f32_e32 v54, 1.0, v54
	v_rcp_f32_e32 v54, v54
	v_add_f32_e32 v56, 1.0, v56
	v_rcp_f32_e32 v59, v56
	v_mul_f32_e32 v54, 0xbf1b4598, v54
	v_mul_f32_e32 v54, 0x3fb8aa3b, v54
	v_exp_f32_e32 v54, v54
	v_add_co_u32_e32 v56, vcc, s3, v52
	v_sub_f32_e32 v54, 1.0, v54
	v_cvt_f16_f32_e32 v54, v54
	v_addc_co_u32_e32 v57, vcc, 0, v53, vcc
	global_store_short v[56:57], v54, off
	v_add_co_u32_e32 v56, vcc, s74, v52
	v_fma_mixlo_f16 v54, v58, v59, 0
	s_nop 0
	v_addc_co_u32_e32 v57, vcc, 0, v53, vcc
	global_store_short v[56:57], v54, off
	v_add_f32_e32 v54, -1.0, v59
	v_fma_f32 v54, v117, v54, 1.0
	v_add_co_u32_e32 v56, vcc, 0x8800000, v52
	v_fma_mixlo_f16 v54, v91, v54, 0
	s_nop 0
	v_addc_co_u32_e32 v57, vcc, 0, v53, vcc
	global_store_short v[56:57], v54, off
	v_cvt_f16_f32_e32 v54, v55
	v_add_co_u32_e32 v52, vcc, 0x9900000, v52
	s_nop 1
	v_addc_co_u32_e32 v53, vcc, 0, v53, vcc
	global_store_short v[52:53], v54, off
	s_cbranch_scc1 .LBB0_435
	s_add_i32 s23, s23, s33
	s_cmpk_lt_i32 s23, 0x440
	s_barrier
	s_cbranch_scc1 .LBB0_419

; __device__ __forceinline__ float bf2f(bf16_t h) { return __uint_as_float((unsigned)h << 16); }
; __device__ __forceinline__ void conv4(const bf16_t* tile, const float* cw, int ch, int tq, float (&o)[4]) {
;   const float w0 = cw[ch], w1 = cw[1536 + ch], w2 = cw[3072 + ch];
;   float xs[6];
; #pragma unroll
;   for (int i = 0; i < 6; ++i) xs[i] = bf2f(tile[(tq * 4 + i) * RPS + ch]);
; #pragma unroll
;   for (int j = 0; j < 4; ++j) o[j] = w0 * xs[j] + w1 * xs[j + 1] + w2 * xs[j + 2];
; }
; __device__ __forceinline__ void rwkv_prep_item(const int wv_, KPR p, int l, int item, bf16_t* tile) {
;     ...
;   for (int nt = 0; nt < 4; ++nt) { const int c = wid * 64 + nt * 16 + cl;
;     f32x4 accw[2], acca[2], accg = (f32x4){0.f, 0.f, 0.f, 0.f};
; #pragma unroll
;     for (int d = 0; d < 2; ++d) { accw[d] = (f32x4){0.f, 0.f, 0.f, 0.f}; acca[d] = (f32x4){0.f, 0.f, 0.f, 0.f};
; #pragma unroll
;       for (int ks = 0; ks < 2; ++ks) {
;         accw[d] = __builtin_amdgcn_mfma_f32_16x16x32_bf16(aw[d][ks], ld_frag(W2T + ((size_t)d * C + c) * 64 + ks * 32 + tq * 8), accw[d], 0, 0, 0);
;         acca[d] = __builtin_amdgcn_mfma_f32_16x16x32_bf16(aa[d][ks], ld_frag(A2T + ((size_t)d * C + c) * 64 + ks * 32 + tq * 8), acca[d], 0, 0, 0); } }
; #pragma unroll
;     for (int ks = 0; ks < 4; ++ks) accg = __builtin_amdgcn_mfma_f32_16x16x32_bf16(ag[ks], ld_frag(G2T + (size_t)c * 128 + ks * 32 + tq * 8), accg, 0, 0, 0);
;     float r4[4], k4[4], v4[4]; conv4(tile, cw, c, tq, r4); conv4(tile, cw, 512 + c, tq, k4); conv4(tile, cw, 1024 + c, tq, v4);
.LBB0_457:
	v_ashrrev_i32_e32 v85, 31, v84
	v_lshlrev_b64 v[52:53], 7, v[84:85]
	v_lshl_add_u64 v[90:91], v[0:1], 0, v[52:53]
	v_lshl_add_u64 v[92:93], v[72:73], 0, v[52:53]
	v_lshl_add_u64 v[238:239], v[90:91], 0, s[92:93]
	v_lshl_add_u64 v[240:241], v[92:93], 0, s[92:93]
	v_lshlrev_b64 v[52:53], 8, v[84:85]
	v_lshl_add_u64 v[124:125], v[74:75], 0, v[52:53]
	global_load_dwordx4 v[190:193], v[90:91], off
	global_load_dwordx4 v[194:197], v[90:91], off offset:64
	global_load_dwordx4 v[198:201], v[92:93], off
	global_load_dwordx4 v[202:205], v[92:93], off offset:64
	global_load_dwordx4 v[206:209], v[238:239], off
	global_load_dwordx4 v[210:213], v[238:239], off offset:64
	global_load_dwordx4 v[214:217], v[240:241], off
	global_load_dwordx4 v[218:221], v[240:241], off offset:64
	global_load_dwordx4 v[222:225], v[124:125], off
	global_load_dwordx4 v[226:229], v[124:125], off offset:64
	global_load_dwordx4 v[230:233], v[124:125], off offset:128
	global_load_dwordx4 v[234:237], v[124:125], off offset:192
	v_add_u32_e32 v106, s20, v3
	s_add_i32 s20, s20, 32
	s_cmpk_lg_i32 s20, 0x80
	s_waitcnt vmcnt(11)
	v_mfma_f32_16x16x32_bf16 v[68:71], v[4:7], v[190:193], 0
	s_waitcnt vmcnt(10)
	v_mfma_f32_16x16x32_bf16 v[68:71], v[12:15], v[194:197], v[68:71]
	s_waitcnt vmcnt(9)
	v_mfma_f32_16x16x32_bf16 v[64:67], v[8:11], v[198:201], 0
	s_waitcnt vmcnt(8)
	v_mfma_f32_16x16x32_bf16 v[64:67], v[16:19], v[202:205], v[64:67]
	s_waitcnt vmcnt(7)
	v_mfma_f32_16x16x32_bf16 v[60:63], v[20:23], v[206:209], 0
	s_waitcnt vmcnt(6)
	v_mfma_f32_16x16x32_bf16 v[60:63], v[28:31], v[210:213], v[60:63]
	s_waitcnt vmcnt(5)
	v_mfma_f32_16x16x32_bf16 v[56:59], v[24:27], v[214:217], 0
	s_waitcnt vmcnt(4)
	v_mfma_f32_16x16x32_bf16 v[56:59], v[32:35], v[218:221], v[56:59]
	s_waitcnt vmcnt(3)
	v_mfma_f32_16x16x32_bf16 v[52:55], v[36:39], v[222:225], 0
	s_waitcnt vmcnt(2)
	v_mfma_f32_16x16x32_bf16 v[52:55], v[40:43], v[226:229], v[52:55]
	s_waitcnt vmcnt(1)
	v_mfma_f32_16x16x32_bf16 v[52:55], v[44:47], v[230:233], v[52:55]
	v_lshl_add_u64 v[94:95], v[84:85], 2, s[4:5]
	v_add_co_u32_e32 v96, vcc, s52, v94
	s_waitcnt vmcnt(0)
	v_mfma_f32_16x16x32_bf16 v[52:55], v[48:51], v[234:237], v[52:55]
	v_addc_co_u32_e32 v97, vcc, 0, v95, vcc
	global_load_dword v93, v[96:97], off offset:2048
	global_load_dword v91, v[94:95], off
	ds_read_u16 v92, v106
	v_add_co_u32_e32 v100, vcc, s54, v94
	s_nop 2
	v_cvt_f16_f32_e32 v52, v52
	v_addc_co_u32_e32 v101, vcc, 0, v95, vcc
	s_waitcnt lgkmcnt(0)
	v_lshlrev_b32_e32 v99, 16, v92
	ds_read_u16 v92, v106 offset:3104
	v_add_co_u32_e32 v102, vcc, s80, v94
	v_cvt_f16_f32_e32 v54, v54
	s_nop 0
	v_addc_co_u32_e32 v103, vcc, 0, v95, vcc
	s_waitcnt lgkmcnt(0)
	v_lshlrev_b32_e32 v104, 16, v92
	ds_read_u16 v92, v106 offset:6208
	global_load_dword v90, v[102:103], off offset:-4096
	global_load_dword v111, v[94:95], off offset:2048
	s_waitcnt lgkmcnt(0)
	v_lshlrev_b32_e32 v107, 16, v92
	ds_read_u16 v92, v106 offset:9312
	s_waitcnt lgkmcnt(0)
	v_lshlrev_b32_e32 v108, 16, v92
	ds_read_u16 v92, v106 offset:12416
	s_waitcnt lgkmcnt(0)
	v_lshlrev_b32_e32 v98, 16, v92
	ds_read_u16 v92, v106 offset:15520
	s_waitcnt lgkmcnt(0)
	v_lshlrev_b32_e32 v92, 16, v92
	s_waitcnt vmcnt(3)
	v_mul_f32_e32 v110, v93, v107
	v_mul_f32_e32 v109, v93, v104
	s_waitcnt vmcnt(2)
	v_fmac_f32_e32 v110, v91, v104
	v_add_co_u32_e32 v104, vcc, s63, v94
	v_fmac_f32_e32 v109, v91, v99
	v_mul_f32_e32 v99, v93, v108
	v_mul_f32_e32 v93, v93, v98
	v_addc_co_u32_e32 v105, vcc, 0, v95, vcc
	v_fmac_f32_e32 v99, v91, v107
	v_fmac_f32_e32 v93, v91, v108
	global_load_dword v91, v[104:105], off
	global_load_dword v94, v[100:101], off offset:2048
	ds_read_u16 v95, v106 offset:1024
	ds_read_u16 v100, v106 offset:4128
	s_waitcnt vmcnt(3)
	v_fma_mixlo_f16 v107, v90, v107, v109
	s_waitcnt lgkmcnt(1)
	v_lshlrev_b32_e32 v95, 16, v95
	s_waitcnt lgkmcnt(0)
	v_lshlrev_b32_e32 v101, 16, v100
	ds_read_u16 v100, v106 offset:7232
	s_waitcnt lgkmcnt(0)
	v_lshlrev_b32_e32 v112, 16, v100
	ds_read_u16 v100, v106 offset:10336
	s_waitcnt lgkmcnt(0)
	v_lshlrev_b32_e32 v113, 16, v100
	ds_read_u16 v100, v106 offset:13440
	s_waitcnt lgkmcnt(0)
	v_lshlrev_b32_e32 v114, 16, v100
	ds_read_u16 v100, v106 offset:16544
	s_waitcnt lgkmcnt(0)
	v_lshlrev_b32_e32 v115, 16, v100
	s_waitcnt vmcnt(1)
	v_mul_f32_e32 v116, v91, v101
	v_fmac_f32_e32 v116, v111, v95
	v_mul_f32_e32 v100, v91, v112
	v_mul_f32_e32 v95, v91, v113
	v_mul_f32_e32 v91, v91, v114
	v_fmac_f32_e32 v100, v111, v101
	v_fmac_f32_e32 v95, v111, v112
	v_fmac_f32_e32 v91, v111, v113
	s_waitcnt vmcnt(0)
	v_fmac_f32_e32 v116, v94, v112
	v_fmac_f32_e32 v100, v94, v113
	v_fmac_f32_e32 v95, v94, v114
	v_fmac_f32_e32 v91, v94, v115
	global_load_dword v111, v[96:97], off
	s_nop 0
	global_load_dword v97, v[104:105], off offset:2048
	global_load_dword v94, v[102:103], off
	ds_read_u16 v96, v106 offset:2048
	s_waitcnt lgkmcnt(0)
	v_lshlrev_b32_e32 v102, 16, v96
	ds_read_u16 v96, v106 offset:5152
	s_waitcnt lgkmcnt(0)
	v_lshlrev_b32_e32 v103, 16, v96
	ds_read_u16 v96, v106 offset:8256
	s_waitcnt lgkmcnt(0)
	v_lshlrev_b32_e32 v112, 16, v96
	ds_read_u16 v96, v106 offset:11360
	s_waitcnt lgkmcnt(0)
	v_lshlrev_b32_e32 v113, 16, v96
	ds_read_u16 v96, v106 offset:14464
	s_waitcnt lgkmcnt(0)
	v_lshlrev_b32_e32 v101, 16, v96
	ds_read_u16 v96, v106 offset:17568
	s_waitcnt lgkmcnt(0)
	v_lshlrev_b32_e32 v96, 16, v96
	s_waitcnt vmcnt(1)
; __device__ __forceinline__ float sigm(float x) { return __builtin_amdgcn_rcpf(1.f + __expf(-x)); }
; #define p (kparams())
; __device__ __forceinline__ void rwkv_prep_item(const int wv_, KPR p, int l, int item, bf16_t* tile) {
;     ...
;     float r4[4], k4[4], v4[4]; conv4(tile, cw, c, tq, r4); conv4(tile, cw, 512 + c, tq, k4); conv4(tile, cw, 1024 + c, tq, v4);
;     const float kkw = p->in[I_RWKK][l * C + c];
;     const float ka = p->in[I_RWKA][l * C + c];
;     const float w00 = p->in[I_RWW0][(l * 2 + 0) * C + c], w01 = p->in[I_RWW0][(l * 2 + 1) * C + c];
;     const float a00 = p->in[I_RWA0][(l * 2 + 0) * C + c], a01 = p->in[I_RWA0][(l * 2 + 1) * C + c];
; #pragma unroll
;     for (int j = 0; j < 4; ++j) { const size_t o = (size_t)(R0 + tq * 4 + j) * 512 + c;
;       const float kn = k4[j] * kkw * inv[j];
;       PRE[0 * AE + o] = f2h(r4[j]); PRE[1 * AE + o] = f2h(v4[j]); PRE[2 * AE + o] = f2h(kn);
; #pragma unroll
;       for (int d = 0; d < 2; ++d) { const float wpre = (d == 0 ? w00 : w01) + accw[d][j];
;         const float u = 1.f - __expf(-0.6065306597f * sigm(wpre));
;         const float a = sigm((d == 0 ? a00 : a01) + acca[d][j]);
;         PRE[(3 + d) * AE + o] = f2h(u); PRE[(5 + d) * AE + o] = f2h(kn * a); PRE[(7 + d) * AE + o] = f2h(k4[j] * (1.f + (a - 1.f) * ka)); }
;       PRE[9 * AE + o] = f2h(accg[j]); } }
	v_mul_f32_e32 v106, v97, v103
	v_fmac_f32_e32 v106, v111, v102
	v_mul_f32_e32 v114, v97, v112
	v_add_u32_e32 v102, s78, v84
	v_fmac_f32_e32 v114, v111, v103
	v_ashrrev_i32_e32 v103, 31, v102
	v_lshlrev_b64 v[102:103], 2, v[102:103]
	v_lshl_add_u64 v[104:105], s[10:11], 0, v[102:103]
	v_lshl_add_u64 v[102:103], s[12:13], 0, v[102:103]
	global_load_dword v117, v[102:103], off
	v_add_u32_e32 v102, s22, v84
	v_ashrrev_i32_e32 v103, 31, v102
	v_mul_f32_e32 v115, v97, v113
	v_mul_f32_e32 v97, v97, v101
	v_lshlrev_b64 v[102:103], 2, v[102:103]
	v_fmac_f32_e32 v115, v111, v112
	v_fmac_f32_e32 v97, v111, v113
	global_load_dword v111, v[104:105], off
	v_lshl_add_u64 v[104:105], s[14:15], 0, v[102:103]
	global_load_dword v118, v[104:105], off
	global_load_dword v119, v[104:105], off offset:2048
	v_lshl_add_u64 v[102:103], s[18:19], 0, v[102:103]
	global_load_dword v120, v[102:103], off
	global_load_dword v121, v[102:103], off offset:2048
	v_lshl_add_u64 v[102:103], v[84:85], 1, s[16:17]
	v_lshl_add_u64 v[104:105], v[102:103], 0, v[76:77]
	s_waitcnt vmcnt(6)
	v_fma_mixlo_f16 v109, v94, v112, v106
	v_add_co_u32_e32 v106, vcc, s55, v104
	global_store_short v[104:105], v107, off
	s_nop 0
	v_addc_co_u32_e32 v107, vcc, 0, v105, vcc
	global_store_short v[106:107], v109, off
	v_add_co_u32_e32 v106, vcc, s48, v104
	v_add_u32_e32 v84, 16, v84
	s_nop 0
	v_addc_co_u32_e32 v107, vcc, 0, v105, vcc
	s_waitcnt vmcnt(6)
	v_mul_f32_e32 v85, v116, v111
	s_waitcnt vmcnt(5)
	v_add_f32_e32 v68, v68, v118
	v_mul_f32_e32 v68, 0xbfb8aa3b, v68
	v_exp_f32_e32 v68, v68
	s_waitcnt vmcnt(4)
	v_add_f32_e32 v60, v60, v119
	v_mul_f32_e32 v60, 0xbfb8aa3b, v60
	v_exp_f32_e32 v60, v60
	v_add_f32_e32 v68, 1.0, v68
	v_rcp_f32_e32 v68, v68
	s_waitcnt vmcnt(3)
	v_add_f32_e32 v64, v64, v120
	v_add_f32_e32 v60, 1.0, v60
	v_mul_f32_e32 v64, 0xbfb8aa3b, v64
	v_mul_f32_e32 v68, 0xbf1b4598, v68
	v_mul_f32_e32 v68, 0x3fb8aa3b, v68
	v_exp_f32_e32 v68, v68
	v_rcp_f32_e32 v60, v60
	v_exp_f32_e32 v64, v64
	s_waitcnt vmcnt(2)
	v_add_f32_e32 v56, v56, v121
	v_sub_f32_e32 v68, 1.0, v68
	v_mul_f32_e32 v60, 0xbf1b4598, v60
	v_add_f32_e32 v64, 1.0, v64
	v_cvt_f16_f32_e32 v68, v68
	v_mul_f32_e32 v60, 0x3fb8aa3b, v60
	v_mul_f32_e32 v122, v89, v85
	v_fma_mixlo_f16 v85, v89, v85, 0
	v_rcp_f32_e32 v64, v64
	v_exp_f32_e32 v60, v60
	v_mul_f32_e32 v56, 0xbfb8aa3b, v56
	global_store_short v[106:107], v85, off
	v_add_co_u32_e32 v106, vcc, s49, v104
	v_exp_f32_e32 v56, v56
	s_nop 0
	v_addc_co_u32_e32 v107, vcc, 0, v105, vcc
	global_store_short v[106:107], v68, off
	v_add_co_u32_e32 v106, vcc, s60, v104
	v_fma_mixlo_f16 v68, v122, v64, 0
	s_nop 0
	v_addc_co_u32_e32 v107, vcc, 0, v105, vcc
	v_add_f32_e32 v64, -1.0, v64
	v_sub_f32_e32 v60, 1.0, v60
	global_store_short v[106:107], v68, off
	v_fma_f32 v64, v117, v64, 1.0
	v_add_co_u32_e32 v106, vcc, s61, v104
	v_add_f32_e32 v56, 1.0, v56
	v_cvt_f16_f32_e32 v60, v60
	v_fma_mixlo_f16 v64, v116, v64, 0
	v_addc_co_u32_e32 v107, vcc, 0, v105, vcc
	v_rcp_f32_e32 v56, v56
	global_store_short v[106:107], v64, off
	v_add_co_u32_e32 v106, vcc, s3, v104
	s_nop 1
	v_addc_co_u32_e32 v107, vcc, 0, v105, vcc
	global_store_short v[106:107], v60, off
	v_add_co_u32_e32 v106, vcc, s74, v104
	v_fma_mixlo_f16 v60, v122, v56, 0
	s_nop 0
	v_addc_co_u32_e32 v107, vcc, 0, v105, vcc
	global_store_short v[106:107], v60, off
	v_add_co_u32_e32 v106, vcc, s65, v104
	v_add_f32_e32 v56, -1.0, v56
	s_nop 0
	v_addc_co_u32_e32 v107, vcc, 0, v105, vcc
	v_add_co_u32_e32 v104, vcc, s62, v104
	v_fma_f32 v56, v117, v56, 1.0
	s_nop 0
	v_addc_co_u32_e32 v105, vcc, 0, v105, vcc
	v_fma_mixlo_f16 v56, v116, v56, 0
	global_store_short v[104:105], v52, off
	v_lshl_add_u64 v[104:105], v[102:103], 0, v[78:79]
	global_store_short v[106:107], v56, off
	v_fma_mixlo_f16 v56, v90, v108, v110
	v_add_co_u32_e32 v106, vcc, s55, v104
	global_store_short v[104:105], v56, off
	v_fma_mixlo_f16 v56, v94, v113, v114
	v_addc_co_u32_e32 v107, vcc, 0, v105, vcc
	v_mul_f32_e32 v52, v100, v111
	global_store_short v[106:107], v56, off
	v_add_co_u32_e32 v106, vcc, s48, v104
	v_mul_f32_e32 v60, v88, v52
	v_fma_mixlo_f16 v52, v88, v52, 0
	v_addc_co_u32_e32 v107, vcc, 0, v105, vcc
	global_store_short v[106:107], v52, off
	v_add_f32_e32 v52, v69, v118
	v_mul_f32_e32 v52, 0xbfb8aa3b, v52
	v_exp_f32_e32 v52, v52
	v_add_f32_e32 v56, v65, v120
	v_mul_f32_e32 v56, 0xbfb8aa3b, v56
	v_exp_f32_e32 v56, v56
	v_add_f32_e32 v52, 1.0, v52
	v_rcp_f32_e32 v52, v52
	v_add_co_u32_e32 v64, vcc, s49, v104
	v_add_f32_e32 v56, 1.0, v56
	v_mul_f32_e32 v52, 0xbf1b4598, v52
	v_mul_f32_e32 v52, 0x3fb8aa3b, v52
	v_exp_f32_e32 v52, v52
	v_rcp_f32_e32 v56, v56
	v_addc_co_u32_e32 v65, vcc, 0, v105, vcc
	v_sub_f32_e32 v52, 1.0, v52
	v_cvt_f16_f32_e32 v52, v52
	global_store_short v[64:65], v52, off
	v_add_co_u32_e32 v64, vcc, s60, v104
	v_fma_mixlo_f16 v52, v60, v56, 0
	s_nop 0
	v_addc_co_u32_e32 v65, vcc, 0, v105, vcc
	global_store_short v[64:65], v52, off
	v_add_f32_e32 v52, -1.0, v56
	v_fma_f32 v52, v117, v52, 1.0
	v_add_co_u32_e32 v64, vcc, s61, v104
	v_fma_mixlo_f16 v52, v100, v52, 0
	s_nop 0
	v_addc_co_u32_e32 v65, vcc, 0, v105, vcc
	global_store_short v[64:65], v52, off
	v_add_f32_e32 v52, v61, v119
	v_mul_f32_e32 v52, 0xbfb8aa3b, v52
	v_exp_f32_e32 v52, v52
	v_add_f32_e32 v56, v57, v121
	v_mul_f32_e32 v56, 0xbfb8aa3b, v56
	v_exp_f32_e32 v56, v56
	v_add_f32_e32 v52, 1.0, v52
	v_rcp_f32_e32 v52, v52
	v_fma_mixlo_f16 v64, v94, v101, v115
	v_add_f32_e32 v56, 1.0, v56
	v_rcp_f32_e32 v61, v56
	v_mul_f32_e32 v52, 0xbf1b4598, v52
	v_mul_f32_e32 v52, 0x3fb8aa3b, v52
	v_exp_f32_e32 v52, v52
	v_add_co_u32_e32 v56, vcc, s3, v104
	v_sub_f32_e32 v52, 1.0, v52
; __device__ __forceinline__ float sigm(float x) { return __builtin_amdgcn_rcpf(1.f + __expf(-x)); }
; __device__ __forceinline__ void rwkv_prep_item(const int wv_, KPR p, int l, int item, bf16_t* tile) {
;     ...
; #pragma unroll
;     for (int j = 0; j < 4; ++j) { const size_t o = (size_t)(R0 + tq * 4 + j) * 512 + c;
;       const float kn = k4[j] * kkw * inv[j];
;       PRE[0 * AE + o] = f2h(r4[j]); PRE[1 * AE + o] = f2h(v4[j]); PRE[2 * AE + o] = f2h(kn);
; #pragma unroll
;       for (int d = 0; d < 2; ++d) { const float wpre = (d == 0 ? w00 : w01) + accw[d][j];
;         const float u = 1.f - __expf(-0.6065306597f * sigm(wpre));
;         const float a = sigm((d == 0 ? a00 : a01) + acca[d][j]);
;         PRE[(3 + d) * AE + o] = f2h(u); PRE[(5 + d) * AE + o] = f2h(kn * a); PRE[(7 + d) * AE + o] = f2h(k4[j] * (1.f + (a - 1.f) * ka)); }
;       PRE[9 * AE + o] = f2h(accg[j]); } }
	v_cvt_f16_f32_e32 v52, v52
	v_addc_co_u32_e32 v57, vcc, 0, v105, vcc
	global_store_short v[56:57], v52, off
	v_add_co_u32_e32 v56, vcc, s74, v104
	v_fma_mixlo_f16 v52, v60, v61, 0
	s_nop 0
	v_addc_co_u32_e32 v57, vcc, 0, v105, vcc
	global_store_short v[56:57], v52, off
	v_add_f32_e32 v52, -1.0, v61
	v_fma_f32 v52, v117, v52, 1.0
	v_add_co_u32_e32 v56, vcc, s65, v104
	v_fma_mixlo_f16 v52, v100, v52, 0
	s_nop 0
	v_addc_co_u32_e32 v57, vcc, 0, v105, vcc
	global_store_short v[56:57], v52, off
	v_cvt_f16_f32_e32 v56, v53
	v_add_co_u32_e32 v52, vcc, s62, v104
	v_mul_f32_e32 v60, v95, v111
	s_nop 0
	v_addc_co_u32_e32 v53, vcc, 0, v105, vcc
	global_store_short v[52:53], v56, off
	v_fma_mixlo_f16 v56, v90, v98, v99
	v_lshl_add_u64 v[52:53], v[102:103], 0, v[80:81]
	global_store_short v[52:53], v56, off
	v_add_co_u32_e32 v56, vcc, s55, v52
	v_mul_f32_e32 v61, v87, v60
	s_nop 0
	v_addc_co_u32_e32 v57, vcc, 0, v53, vcc
	global_store_short v[56:57], v64, off
	v_add_co_u32_e32 v56, vcc, s48, v52
	v_fma_mixlo_f16 v60, v87, v60, 0
	s_nop 0
	v_addc_co_u32_e32 v57, vcc, 0, v53, vcc
	global_store_short v[56:57], v60, off
	v_add_f32_e32 v56, v70, v118
	v_mul_f32_e32 v56, 0xbfb8aa3b, v56
	v_exp_f32_e32 v56, v56
	v_add_f32_e32 v57, v66, v120
	v_mul_f32_e32 v57, 0xbfb8aa3b, v57
	v_exp_f32_e32 v57, v57
	v_add_f32_e32 v56, 1.0, v56
	v_rcp_f32_e32 v56, v56
	v_add_f32_e32 v57, 1.0, v57
	v_rcp_f32_e32 v60, v57
	v_mul_f32_e32 v56, 0xbf1b4598, v56
	v_mul_f32_e32 v56, 0x3fb8aa3b, v56
	v_exp_f32_e32 v56, v56
	s_nop 0
	v_sub_f32_e32 v56, 1.0, v56
	v_cvt_f16_f32_e32 v64, v56
	v_add_co_u32_e32 v56, vcc, s49, v52
	s_nop 1
	v_addc_co_u32_e32 v57, vcc, 0, v53, vcc
	global_store_short v[56:57], v64, off
	v_add_co_u32_e32 v56, vcc, s60, v52
	v_fma_mixlo_f16 v64, v61, v60, 0
	s_nop 0
	v_addc_co_u32_e32 v57, vcc, 0, v53, vcc
	global_store_short v[56:57], v64, off
	v_add_f32_e32 v56, -1.0, v60
	v_fma_f32 v56, v117, v56, 1.0
	v_fma_mixlo_f16 v60, v95, v56, 0
	v_add_co_u32_e32 v56, vcc, s61, v52
	s_nop 1
	v_addc_co_u32_e32 v57, vcc, 0, v53, vcc
	global_store_short v[56:57], v60, off
	v_add_f32_e32 v56, v62, v119
	v_mul_f32_e32 v56, 0xbfb8aa3b, v56
	v_exp_f32_e32 v56, v56
	v_add_f32_e32 v57, v58, v121
	v_mul_f32_e32 v57, 0xbfb8aa3b, v57
	v_exp_f32_e32 v57, v57
	v_add_f32_e32 v56, 1.0, v56
	v_rcp_f32_e32 v56, v56
	v_add_f32_e32 v57, 1.0, v57
	v_rcp_f32_e32 v58, v57
	v_mul_f32_e32 v56, 0xbf1b4598, v56
	v_mul_f32_e32 v56, 0x3fb8aa3b, v56
	v_exp_f32_e32 v56, v56
	s_nop 0
	v_sub_f32_e32 v56, 1.0, v56
	v_cvt_f16_f32_e32 v60, v56
	v_add_co_u32_e32 v56, vcc, s3, v52
	s_nop 1
	v_addc_co_u32_e32 v57, vcc, 0, v53, vcc
	global_store_short v[56:57], v60, off
	v_add_co_u32_e32 v56, vcc, s74, v52
	v_fma_mixlo_f16 v60, v61, v58, 0
	s_nop 0
	v_addc_co_u32_e32 v57, vcc, 0, v53, vcc
	global_store_short v[56:57], v60, off
	v_add_f32_e32 v56, -1.0, v58
	v_fma_f32 v56, v117, v56, 1.0
	v_fma_mixlo_f16 v58, v95, v56, 0
	v_add_co_u32_e32 v56, vcc, s65, v52
	v_fma_mixlo_f16 v60, v94, v96, v97
	s_nop 0
	v_addc_co_u32_e32 v57, vcc, 0, v53, vcc
	v_add_co_u32_e32 v52, vcc, s62, v52
	global_store_short v[56:57], v58, off
	s_nop 0
	v_addc_co_u32_e32 v53, vcc, 0, v53, vcc
	global_store_short v[52:53], v54, off
	v_fma_mixlo_f16 v56, v90, v92, v93
	v_lshl_add_u64 v[52:53], v[102:103], 0, v[82:83]
	global_store_short v[52:53], v56, off
	v_add_co_u32_e32 v56, vcc, s55, v52
	v_mul_f32_e32 v54, v91, v111
	s_nop 0
	v_addc_co_u32_e32 v57, vcc, 0, v53, vcc
	global_store_short v[56:57], v60, off
	v_add_co_u32_e32 v56, vcc, s48, v52
	v_mul_f32_e32 v58, v86, v54
	v_fma_mixlo_f16 v54, v86, v54, 0
	v_addc_co_u32_e32 v57, vcc, 0, v53, vcc
	global_store_short v[56:57], v54, off
	v_add_f32_e32 v54, v71, v118
	v_mul_f32_e32 v54, 0xbfb8aa3b, v54
	v_exp_f32_e32 v54, v54
	v_add_f32_e32 v56, v67, v120
	v_mul_f32_e32 v56, 0xbfb8aa3b, v56
	v_exp_f32_e32 v56, v56
	v_add_f32_e32 v54, 1.0, v54
	v_rcp_f32_e32 v54, v54
	v_add_f32_e32 v56, 1.0, v56
	v_rcp_f32_e32 v60, v56
	v_mul_f32_e32 v54, 0xbf1b4598, v54
	v_mul_f32_e32 v54, 0x3fb8aa3b, v54
	v_exp_f32_e32 v54, v54
	v_add_co_u32_e32 v56, vcc, s49, v52
	v_sub_f32_e32 v54, 1.0, v54
	v_cvt_f16_f32_e32 v54, v54
	v_addc_co_u32_e32 v57, vcc, 0, v53, vcc
	global_store_short v[56:57], v54, off
	v_add_co_u32_e32 v56, vcc, s60, v52
	v_fma_mixlo_f16 v54, v58, v60, 0
	s_nop 0
	v_addc_co_u32_e32 v57, vcc, 0, v53, vcc
	global_store_short v[56:57], v54, off
	v_add_f32_e32 v54, -1.0, v60
	v_fma_f32 v54, v117, v54, 1.0
	v_add_co_u32_e32 v56, vcc, s61, v52
	v_fma_mixlo_f16 v54, v91, v54, 0
	s_nop 0
	v_addc_co_u32_e32 v57, vcc, 0, v53, vcc
	global_store_short v[56:57], v54, off
	v_add_f32_e32 v54, v63, v119
	v_mul_f32_e32 v54, 0xbfb8aa3b, v54
	v_exp_f32_e32 v54, v54
	v_add_f32_e32 v56, v59, v121
	v_mul_f32_e32 v56, 0xbfb8aa3b, v56
	v_exp_f32_e32 v56, v56
	v_add_f32_e32 v54, 1.0, v54
	v_rcp_f32_e32 v54, v54
	v_add_f32_e32 v56, 1.0, v56
	v_rcp_f32_e32 v59, v56
	v_mul_f32_e32 v54, 0xbf1b4598, v54
	v_mul_f32_e32 v54, 0x3fb8aa3b, v54
	v_exp_f32_e32 v54, v54
	v_add_co_u32_e32 v56, vcc, s3, v52
	v_sub_f32_e32 v54, 1.0, v54
	v_cvt_f16_f32_e32 v54, v54
	v_addc_co_u32_e32 v57, vcc, 0, v53, vcc
	global_store_short v[56:57], v54, off
	v_add_co_u32_e32 v56, vcc, s74, v52
	v_fma_mixlo_f16 v54, v58, v59, 0
	s_nop 0
	v_addc_co_u32_e32 v57, vcc, 0, v53, vcc
	global_store_short v[56:57], v54, off
	v_add_f32_e32 v54, -1.0, v59
	v_fma_f32 v54, v117, v54, 1.0
	v_add_co_u32_e32 v56, vcc, 0x8800000, v52
	v_fma_mixlo_f16 v54, v91, v54, 0
	s_nop 0
	v_addc_co_u32_e32 v57, vcc, 0, v53, vcc
	global_store_short v[56:57], v54, off
	v_cvt_f16_f32_e32 v54, v55
	v_add_co_u32_e32 v52, vcc, 0x9900000, v52
	s_nop 1
	v_addc_co_u32_e32 v53, vcc, 0, v53, vcc
	global_store_short v[52:53], v54, off
	s_cbranch_scc1 .LBB0_457
	s_add_i32 s23, s23, 1
	s_cmp_lg_u32 s23, 3
	s_barrier
	s_cbranch_scc1 .LBB0_441

; __device__ __forceinline__ float lo16(unsigned u) { return __uint_as_float(u << 16); }
; __device__ __forceinline__ float hi16(unsigned u) { return __uint_as_float(u & 0xffff0000u); }
; __device__ __forceinline__ unsigned pk2(float lo, float hi) { f32x2n v = {lo, hi}; bf16x2n b = __builtin_convertvector(v, bf16x2n); return __builtin_bit_cast(unsigned, b); }
; __device__ __forceinline__ float sigm(float x) { return __builtin_amdgcn_rcpf(1.f + __expf(-x)); }
; __device__ __forceinline__ float tanh_fast(float x) { float e = __expf(2.f * x); return 1.f - 2.f * __builtin_amdgcn_rcpf(e + 1.f); }
; #define p (kparams())
; template <int MODE>
; __device__ __forceinline__ bf16x8 xf_frag(const bf16_t* p) {
;   const u32x4 u = *(const u32x4*)p;
;   if (MODE == 0) return __builtin_bit_cast(bf16x8, u);
;   float f[8] = {lo16(u.x), hi16(u.x), lo16(u.y), hi16(u.y), lo16(u.z), hi16(u.z), lo16(u.w), hi16(u.w)};
; #pragma unroll
;   for (int e = 0; e < 8; ++e) f[e] = MODE == 1 ? tanh_fast(f[e]) : sigm(f[e]);
;   u32x4 o; o.x = pk2(f[0], f[1]); o.y = pk2(f[2], f[3]); o.z = pk2(f[4], f[5]); o.w = pk2(f[6], f[7]);
;   return __builtin_bit_cast(bf16x8, o);
; __device__ __forceinline__ void rwkv_prep_item(const int wv_, KPR p, int l, int item, bf16_t* tile) {
;     ...
;   float inv[4];
; #pragma unroll
;   for (int j = 0; j < 4; ++j) { inv[j] = rsqrtf(rowsum16(ss[j]) + 1e-12f); const float r = rowsum16(rk[j]); if (cl == 0) RK[(size_t)(R0 + tq * 4 + j) * 8 + wid] = r; }
;   const bf16_t* arow = PNG + (size_t)(R0 + cl) * NNGP;
;   bf16x8 aw[2][2], aa[2][2], ag[4];
; #pragma unroll
;   for (int d = 0; d < 2; ++d)
; #pragma unroll
;     for (int ks = 0; ks < 2; ++ks) { aw[d][ks] = xf_frag<1>(arow + O_WL + d * 64 + ks * 32 + tq * 8); aa[d][ks] = xf_frag<0>(arow + O_AL + d * 64 + ks * 32 + tq * 8); }
; #pragma unroll
;   for (int ks = 0; ks < 4; ++ks) ag[ks] = xf_frag<2>(arow + O_GL + ks * 32 + tq * 8);
.LBB0_476:
	s_or_b64 exec, exec, s[18:19]
	v_add_f32_e32 v0, v1, v4
	v_add_f32_e32 v0, 0x2b8cbccc, v0
	v_cmp_gt_f32_e32 vcc, s96, v0
	v_mul_f32_e32 v1, 0x4b800000, v0
	v_or_b32_e32 v4, s23, v60
	v_cndmask_b32_e32 v0, v0, v1, vcc
	v_rsq_f32_e32 v0, v0
	v_lshlrev_b64 v[76:77], 10, v[52:53]
	v_lshlrev_b64 v[78:79], 10, v[54:55]
	v_lshlrev_b64 v[80:81], 10, v[56:57]
	v_mul_f32_e32 v1, 0x45800000, v0
	v_cndmask_b32_e32 v86, v0, v1, vcc
	v_add_f32_e32 v0, v5, v6
	v_add_f32_e32 v0, 0x2b8cbccc, v0
	v_cmp_gt_f32_e32 vcc, s96, v0
	v_mul_f32_e32 v1, 0x4b800000, v0
	v_lshlrev_b64 v[82:83], 10, v[58:59]
	v_cndmask_b32_e32 v0, v0, v1, vcc
	v_rsq_f32_e32 v0, v0
	v_add_u32_e32 v84, v61, v60
	s_mov_b32 s20, 0
	v_mul_f32_e32 v1, 0x45800000, v0
	v_cndmask_b32_e32 v87, v0, v1, vcc
	v_add_f32_e32 v0, v7, v8
	v_add_f32_e32 v0, 0x2b8cbccc, v0
	v_cmp_gt_f32_e32 vcc, s96, v0
	v_mul_f32_e32 v1, 0x4b800000, v0
	s_nop 0
	v_cndmask_b32_e32 v0, v0, v1, vcc
	v_rsq_f32_e32 v0, v0
	s_nop 0
	v_mul_f32_e32 v1, 0x45800000, v0
	v_cndmask_b32_e32 v88, v0, v1, vcc
	v_add_f32_e32 v0, v9, v13
	v_add_f32_e32 v0, 0x2b8cbccc, v0
	v_cmp_gt_f32_e32 vcc, s96, v0
	v_mul_f32_e32 v1, 0x4b800000, v0
	s_nop 0
	v_cndmask_b32_e32 v0, v0, v1, vcc
	v_rsq_f32_e32 v0, v0
	s_nop 0
	v_mul_f32_e32 v1, 0x45800000, v0
	v_cndmask_b32_e32 v89, v0, v1, vcc
	v_mov_b64_e32 v[0:1], s[16:17]
	v_mad_i64_i32 v[4:5], s[16:17], v4, s81, v[0:1]
	v_lshlrev_b32_e32 v0, 4, v12
	v_mov_b32_e32 v1, v2
	v_lshl_add_u64 v[48:49], v[4:5], 0, v[0:1]
	global_load_dwordx4 v[190:193], v[48:49], off offset:3072
	global_load_dwordx4 v[194:197], v[48:49], off offset:3328
	global_load_dwordx4 v[198:201], v[48:49], off offset:3136
	global_load_dwordx4 v[202:205], v[48:49], off offset:3392
	global_load_dwordx4 v[206:209], v[48:49], off offset:3200
	global_load_dwordx4 v[210:213], v[48:49], off offset:3456
	global_load_dwordx4 v[214:217], v[48:49], off offset:3264
	global_load_dwordx4 v[218:221], v[48:49], off offset:3520
	global_load_dwordx4 v[222:225], v[48:49], off offset:3584
	global_load_dwordx4 v[226:229], v[48:49], off offset:3648
	global_load_dwordx4 v[230:233], v[48:49], off offset:3712
	global_load_dwordx4 v[234:237], v[48:49], off offset:3776
	s_waitcnt vmcnt(11)
	v_mov_b64_e32 v[4:5], v[190:191]
	v_mov_b64_e32 v[6:7], v[192:193]
	s_add_u32 s16, s14, 0x2a2e0000
	s_addc_u32 s17, s15, 0
	v_lshlrev_b32_e32 v8, 16, v4
	v_and_b32_e32 v9, 0xffff0000, v4
	v_lshlrev_b32_e32 v10, 16, v5
	v_and_b32_e32 v11, 0xffff0000, v5
	v_lshlrev_b32_e32 v12, 16, v6
	v_and_b32_e32 v13, 0xffff0000, v6
	v_lshlrev_b32_e32 v14, 16, v7
	v_and_b32_e32 v15, 0xffff0000, v7
	v_add_f32_e32 v4, v8, v8
	v_add_f32_e32 v5, v9, v9
	v_add_f32_e32 v6, v10, v10
	v_add_f32_e32 v7, v11, v11
	v_add_f32_e32 v8, v12, v12
	v_add_f32_e32 v9, v13, v13
	v_add_f32_e32 v10, v14, v14
	v_add_f32_e32 v11, v15, v15
	v_mul_f32_e32 v4, 0x3fb8aa3b, v4
	v_mul_f32_e32 v5, 0x3fb8aa3b, v5
	v_mul_f32_e32 v6, 0x3fb8aa3b, v6
	v_mul_f32_e32 v7, 0x3fb8aa3b, v7
	v_mul_f32_e32 v8, 0x3fb8aa3b, v8
	v_mul_f32_e32 v9, 0x3fb8aa3b, v9
	v_mul_f32_e32 v10, 0x3fb8aa3b, v10
	v_mul_f32_e32 v11, 0x3fb8aa3b, v11
	v_exp_f32_e32 v4, v4
	v_exp_f32_e32 v5, v5
	v_exp_f32_e32 v6, v6
	v_exp_f32_e32 v7, v7
	v_exp_f32_e32 v8, v8
	v_exp_f32_e32 v9, v9
	v_exp_f32_e32 v10, v10
	v_exp_f32_e32 v11, v11
	v_add_f32_e32 v4, 1.0, v4
	v_add_f32_e32 v5, 1.0, v5
	v_add_f32_e32 v6, 1.0, v6
	v_add_f32_e32 v7, 1.0, v7
	v_add_f32_e32 v8, 1.0, v8
	v_add_f32_e32 v9, 1.0, v9
	v_add_f32_e32 v10, 1.0, v10
	v_add_f32_e32 v11, 1.0, v11
	v_rcp_f32_e32 v4, v4
	v_rcp_f32_e32 v5, v5
	v_rcp_f32_e32 v6, v6
	v_rcp_f32_e32 v7, v7
	v_rcp_f32_e32 v8, v8
	v_rcp_f32_e32 v9, v9
	v_rcp_f32_e32 v10, v10
	v_rcp_f32_e32 v11, v11
	v_pk_fma_f32 v[4:5], v[4:5], 2.0, 1.0 op_sel_hi:[1,0,0] neg_lo:[1,0,0] neg_hi:[1,0,0]
	v_pk_fma_f32 v[6:7], v[6:7], 2.0, 1.0 op_sel_hi:[1,0,0] neg_lo:[1,0,0] neg_hi:[1,0,0]
	v_pk_fma_f32 v[8:9], v[8:9], 2.0, 1.0 op_sel_hi:[1,0,0] neg_lo:[1,0,0] neg_hi:[1,0,0]
	v_pk_fma_f32 v[10:11], v[10:11], 2.0, 1.0 op_sel_hi:[1,0,0] neg_lo:[1,0,0] neg_hi:[1,0,0]
	v_cvt_pk_bf16_f32 v4, v4, v5
	v_cvt_pk_bf16_f32 v5, v6, v7
	v_cvt_pk_bf16_f32 v6, v8, v9
	v_cvt_pk_bf16_f32 v7, v10, v11
	s_waitcnt vmcnt(10)
	v_mov_b64_e32 v[8:9], v[194:195]
	v_mov_b64_e32 v[10:11], v[196:197]
	s_waitcnt vmcnt(9)
	v_mov_b64_e32 v[12:13], v[198:199]
	v_mov_b64_e32 v[14:15], v[200:201]
	v_lshlrev_b32_e32 v16, 16, v12
	v_and_b32_e32 v17, 0xffff0000, v12
	v_lshlrev_b32_e32 v18, 16, v13
	v_and_b32_e32 v19, 0xffff0000, v13
	v_lshlrev_b32_e32 v20, 16, v14
	v_and_b32_e32 v21, 0xffff0000, v14
	v_lshlrev_b32_e32 v22, 16, v15
	v_and_b32_e32 v23, 0xffff0000, v15
	v_add_f32_e32 v12, v16, v16
	v_add_f32_e32 v13, v17, v17
	v_add_f32_e32 v14, v18, v18
	v_add_f32_e32 v15, v19, v19
	v_add_f32_e32 v16, v20, v20
	v_add_f32_e32 v17, v21, v21
	v_add_f32_e32 v18, v22, v22
	v_add_f32_e32 v19, v23, v23
	v_mul_f32_e32 v12, 0x3fb8aa3b, v12
	v_mul_f32_e32 v13, 0x3fb8aa3b, v13
	v_mul_f32_e32 v14, 0x3fb8aa3b, v14
	v_mul_f32_e32 v15, 0x3fb8aa3b, v15
	v_mul_f32_e32 v16, 0x3fb8aa3b, v16
	v_mul_f32_e32 v17, 0x3fb8aa3b, v17
	v_mul_f32_e32 v18, 0x3fb8aa3b, v18
	v_mul_f32_e32 v19, 0x3fb8aa3b, v19
	v_exp_f32_e32 v12, v12
	v_exp_f32_e32 v13, v13
	v_exp_f32_e32 v14, v14
	v_exp_f32_e32 v15, v15
	v_exp_f32_e32 v16, v16
	v_exp_f32_e32 v17, v17
	v_exp_f32_e32 v18, v18
	v_exp_f32_e32 v19, v19
	v_add_f32_e32 v12, 1.0, v12
	v_add_f32_e32 v13, 1.0, v13
	v_add_f32_e32 v14, 1.0, v14
	v_add_f32_e32 v15, 1.0, v15
	v_add_f32_e32 v16, 1.0, v16
	v_add_f32_e32 v17, 1.0, v17
	v_add_f32_e32 v18, 1.0, v18
	v_add_f32_e32 v19, 1.0, v19
	v_rcp_f32_e32 v12, v12
	v_rcp_f32_e32 v13, v13
	v_rcp_f32_e32 v14, v14
	v_rcp_f32_e32 v15, v15
	v_rcp_f32_e32 v16, v16
	v_rcp_f32_e32 v17, v17
	v_rcp_f32_e32 v18, v18
	v_rcp_f32_e32 v19, v19
	v_pk_fma_f32 v[12:13], v[12:13], 2.0, 1.0 op_sel_hi:[1,0,0] neg_lo:[1,0,0] neg_hi:[1,0,0]
	v_pk_fma_f32 v[14:15], v[14:15], 2.0, 1.0 op_sel_hi:[1,0,0] neg_lo:[1,0,0] neg_hi:[1,0,0]
	v_pk_fma_f32 v[16:17], v[16:17], 2.0, 1.0 op_sel_hi:[1,0,0] neg_lo:[1,0,0] neg_hi:[1,0,0]
	v_pk_fma_f32 v[18:19], v[18:19], 2.0, 1.0 op_sel_hi:[1,0,0] neg_lo:[1,0,0] neg_hi:[1,0,0]
	v_cvt_pk_bf16_f32 v12, v12, v13
	v_cvt_pk_bf16_f32 v13, v14, v15
	v_cvt_pk_bf16_f32 v14, v16, v17
	v_cvt_pk_bf16_f32 v15, v18, v19
	s_waitcnt vmcnt(8)
; __device__ __forceinline__ float lo16(unsigned u) { return __uint_as_float(u << 16); }
; __device__ __forceinline__ float hi16(unsigned u) { return __uint_as_float(u & 0xffff0000u); }
; __device__ __forceinline__ unsigned pk2(float lo, float hi) { f32x2n v = {lo, hi}; bf16x2n b = __builtin_convertvector(v, bf16x2n); return __builtin_bit_cast(unsigned, b); }
; __device__ __forceinline__ float sigm(float x) { return __builtin_amdgcn_rcpf(1.f + __expf(-x)); }
; __device__ __forceinline__ float tanh_fast(float x) { float e = __expf(2.f * x); return 1.f - 2.f * __builtin_amdgcn_rcpf(e + 1.f); }
; #define p (kparams())
; template <int MODE>
; __device__ __forceinline__ bf16x8 xf_frag(const bf16_t* p) {
;   const u32x4 u = *(const u32x4*)p;
;   if (MODE == 0) return __builtin_bit_cast(bf16x8, u);
;   float f[8] = {lo16(u.x), hi16(u.x), lo16(u.y), hi16(u.y), lo16(u.z), hi16(u.z), lo16(u.w), hi16(u.w)};
; #pragma unroll
;   for (int e = 0; e < 8; ++e) f[e] = MODE == 1 ? tanh_fast(f[e]) : sigm(f[e]);
;   u32x4 o; o.x = pk2(f[0], f[1]); o.y = pk2(f[2], f[3]); o.z = pk2(f[4], f[5]); o.w = pk2(f[6], f[7]);
;   return __builtin_bit_cast(bf16x8, o);
; __device__ __forceinline__ void rwkv_prep_item(const int wv_, KPR p, int l, int item, bf16_t* tile) {
;     ...
; #pragma unroll
;   for (int d = 0; d < 2; ++d)
; #pragma unroll
;     for (int ks = 0; ks < 2; ++ks) { aw[d][ks] = xf_frag<1>(arow + O_WL + d * 64 + ks * 32 + tq * 8); aa[d][ks] = xf_frag<0>(arow + O_AL + d * 64 + ks * 32 + tq * 8); }
; #pragma unroll
;   for (int ks = 0; ks < 4; ++ks) ag[ks] = xf_frag<2>(arow + O_GL + ks * 32 + tq * 8);
	v_mov_b64_e32 v[16:17], v[202:203]
	v_mov_b64_e32 v[18:19], v[204:205]
	s_waitcnt vmcnt(7)
	v_mov_b64_e32 v[20:21], v[206:207]
	v_mov_b64_e32 v[22:23], v[208:209]
	v_lshlrev_b32_e32 v24, 16, v20
	v_and_b32_e32 v25, 0xffff0000, v20
	v_lshlrev_b32_e32 v26, 16, v21
	v_and_b32_e32 v27, 0xffff0000, v21
	v_lshlrev_b32_e32 v28, 16, v22
	v_and_b32_e32 v29, 0xffff0000, v22
	v_lshlrev_b32_e32 v30, 16, v23
	v_and_b32_e32 v31, 0xffff0000, v23
	v_add_f32_e32 v20, v24, v24
	v_add_f32_e32 v21, v25, v25
	v_add_f32_e32 v22, v26, v26
	v_add_f32_e32 v23, v27, v27
	v_add_f32_e32 v24, v28, v28
	v_add_f32_e32 v25, v29, v29
	v_add_f32_e32 v26, v30, v30
	v_add_f32_e32 v27, v31, v31
	v_mul_f32_e32 v20, 0x3fb8aa3b, v20
	v_mul_f32_e32 v21, 0x3fb8aa3b, v21
	v_mul_f32_e32 v22, 0x3fb8aa3b, v22
	v_mul_f32_e32 v23, 0x3fb8aa3b, v23
	v_mul_f32_e32 v24, 0x3fb8aa3b, v24
	v_mul_f32_e32 v25, 0x3fb8aa3b, v25
	v_mul_f32_e32 v26, 0x3fb8aa3b, v26
	v_mul_f32_e32 v27, 0x3fb8aa3b, v27
	v_exp_f32_e32 v20, v20
	v_exp_f32_e32 v21, v21
	v_exp_f32_e32 v22, v22
	v_exp_f32_e32 v23, v23
	v_exp_f32_e32 v24, v24
	v_exp_f32_e32 v25, v25
	v_exp_f32_e32 v26, v26
	v_exp_f32_e32 v27, v27
	v_add_f32_e32 v20, 1.0, v20
	v_add_f32_e32 v21, 1.0, v21
	v_add_f32_e32 v22, 1.0, v22
	v_add_f32_e32 v23, 1.0, v23
	v_add_f32_e32 v24, 1.0, v24
	v_add_f32_e32 v25, 1.0, v25
	v_add_f32_e32 v26, 1.0, v26
	v_add_f32_e32 v27, 1.0, v27
	v_rcp_f32_e32 v20, v20
	v_rcp_f32_e32 v21, v21
	v_rcp_f32_e32 v22, v22
	v_rcp_f32_e32 v23, v23
	v_rcp_f32_e32 v24, v24
	v_rcp_f32_e32 v25, v25
	v_rcp_f32_e32 v26, v26
	v_rcp_f32_e32 v27, v27
	v_pk_fma_f32 v[20:21], v[20:21], 2.0, 1.0 op_sel_hi:[1,0,0] neg_lo:[1,0,0] neg_hi:[1,0,0]
	v_pk_fma_f32 v[22:23], v[22:23], 2.0, 1.0 op_sel_hi:[1,0,0] neg_lo:[1,0,0] neg_hi:[1,0,0]
	v_pk_fma_f32 v[24:25], v[24:25], 2.0, 1.0 op_sel_hi:[1,0,0] neg_lo:[1,0,0] neg_hi:[1,0,0]
	v_pk_fma_f32 v[26:27], v[26:27], 2.0, 1.0 op_sel_hi:[1,0,0] neg_lo:[1,0,0] neg_hi:[1,0,0]
	v_cvt_pk_bf16_f32 v20, v20, v21
	v_cvt_pk_bf16_f32 v21, v22, v23
	v_cvt_pk_bf16_f32 v22, v24, v25
	v_cvt_pk_bf16_f32 v23, v26, v27
	s_waitcnt vmcnt(6)
	v_mov_b64_e32 v[24:25], v[210:211]
	v_mov_b64_e32 v[26:27], v[212:213]
	s_waitcnt vmcnt(5)
	v_mov_b64_e32 v[28:29], v[214:215]
	v_mov_b64_e32 v[30:31], v[216:217]
	v_lshlrev_b32_e32 v32, 16, v28
	v_and_b32_e32 v33, 0xffff0000, v28
	v_lshlrev_b32_e32 v34, 16, v29
	v_and_b32_e32 v35, 0xffff0000, v29
	v_lshlrev_b32_e32 v36, 16, v30
	v_and_b32_e32 v37, 0xffff0000, v30
	v_lshlrev_b32_e32 v38, 16, v31
	v_and_b32_e32 v39, 0xffff0000, v31
	v_add_f32_e32 v28, v32, v32
	v_add_f32_e32 v29, v33, v33
	v_add_f32_e32 v30, v34, v34
	v_add_f32_e32 v31, v35, v35
	v_add_f32_e32 v32, v36, v36
	v_add_f32_e32 v33, v37, v37
	v_add_f32_e32 v34, v38, v38
	v_add_f32_e32 v35, v39, v39
	v_mul_f32_e32 v28, 0x3fb8aa3b, v28
	v_mul_f32_e32 v29, 0x3fb8aa3b, v29
	v_mul_f32_e32 v30, 0x3fb8aa3b, v30
	v_mul_f32_e32 v31, 0x3fb8aa3b, v31
	v_mul_f32_e32 v32, 0x3fb8aa3b, v32
	v_mul_f32_e32 v33, 0x3fb8aa3b, v33
	v_mul_f32_e32 v34, 0x3fb8aa3b, v34
	v_mul_f32_e32 v35, 0x3fb8aa3b, v35
	v_exp_f32_e32 v28, v28
	v_exp_f32_e32 v29, v29
	v_exp_f32_e32 v30, v30
	v_exp_f32_e32 v31, v31
	v_exp_f32_e32 v32, v32
	v_exp_f32_e32 v33, v33
	v_exp_f32_e32 v34, v34
	v_exp_f32_e32 v35, v35
	v_add_f32_e32 v28, 1.0, v28
	v_add_f32_e32 v29, 1.0, v29
	v_add_f32_e32 v30, 1.0, v30
	v_add_f32_e32 v31, 1.0, v31
	v_add_f32_e32 v32, 1.0, v32
	v_add_f32_e32 v33, 1.0, v33
	v_add_f32_e32 v34, 1.0, v34
	v_add_f32_e32 v35, 1.0, v35
	v_rcp_f32_e32 v28, v28
	v_rcp_f32_e32 v29, v29
	v_rcp_f32_e32 v30, v30
	v_rcp_f32_e32 v31, v31
	v_rcp_f32_e32 v32, v32
	v_rcp_f32_e32 v33, v33
	v_rcp_f32_e32 v34, v34
	v_rcp_f32_e32 v35, v35
	v_pk_fma_f32 v[28:29], v[28:29], 2.0, 1.0 op_sel_hi:[1,0,0] neg_lo:[1,0,0] neg_hi:[1,0,0]
	v_pk_fma_f32 v[30:31], v[30:31], 2.0, 1.0 op_sel_hi:[1,0,0] neg_lo:[1,0,0] neg_hi:[1,0,0]
	v_pk_fma_f32 v[32:33], v[32:33], 2.0, 1.0 op_sel_hi:[1,0,0] neg_lo:[1,0,0] neg_hi:[1,0,0]
	v_pk_fma_f32 v[34:35], v[34:35], 2.0, 1.0 op_sel_hi:[1,0,0] neg_lo:[1,0,0] neg_hi:[1,0,0]
	v_cvt_pk_bf16_f32 v28, v28, v29
	v_cvt_pk_bf16_f32 v29, v30, v31
	v_cvt_pk_bf16_f32 v30, v32, v33
	v_cvt_pk_bf16_f32 v31, v34, v35
	s_waitcnt vmcnt(4)
	v_mov_b64_e32 v[32:33], v[218:219]
	v_mov_b64_e32 v[34:35], v[220:221]
	s_waitcnt vmcnt(3)
	v_mov_b64_e32 v[36:37], v[222:223]
	v_mov_b64_e32 v[38:39], v[224:225]
	v_lshlrev_b32_e32 v40, 16, v36
	v_and_b32_e32 v36, 0xffff0000, v36
	v_lshlrev_b32_e32 v41, 16, v37
	v_and_b32_e32 v37, 0xffff0000, v37
	v_lshlrev_b32_e32 v42, 16, v38
	v_and_b32_e32 v38, 0xffff0000, v38
	v_lshlrev_b32_e32 v43, 16, v39
	v_and_b32_e32 v39, 0xffff0000, v39
	v_mul_f32_e32 v40, 0xbfb8aa3b, v40
	v_mul_f32_e32 v36, 0xbfb8aa3b, v36
	v_mul_f32_e32 v41, 0xbfb8aa3b, v41
	v_mul_f32_e32 v37, 0xbfb8aa3b, v37
	v_mul_f32_e32 v42, 0xbfb8aa3b, v42
	v_mul_f32_e32 v38, 0xbfb8aa3b, v38
	v_mul_f32_e32 v43, 0xbfb8aa3b, v43
	v_mul_f32_e32 v39, 0xbfb8aa3b, v39
	v_exp_f32_e32 v40, v40
	v_exp_f32_e32 v36, v36
	v_exp_f32_e32 v41, v41
	v_exp_f32_e32 v37, v37
	v_exp_f32_e32 v42, v42
	v_exp_f32_e32 v38, v38
	v_exp_f32_e32 v43, v43
	v_exp_f32_e32 v39, v39
	v_add_f32_e32 v40, 1.0, v40
	v_add_f32_e32 v36, 1.0, v36
	v_add_f32_e32 v41, 1.0, v41
	v_add_f32_e32 v37, 1.0, v37
	v_add_f32_e32 v42, 1.0, v42
	v_add_f32_e32 v38, 1.0, v38
	v_add_f32_e32 v43, 1.0, v43
	v_add_f32_e32 v39, 1.0, v39
	v_rcp_f32_e32 v40, v40
	v_rcp_f32_e32 v36, v36
	v_rcp_f32_e32 v41, v41
	v_rcp_f32_e32 v37, v37
	v_rcp_f32_e32 v42, v42
	v_rcp_f32_e32 v38, v38
	v_rcp_f32_e32 v43, v43
	v_rcp_f32_e32 v39, v39
	v_cvt_pk_bf16_f32 v36, v40, v36
	v_cvt_pk_bf16_f32 v37, v41, v37
	v_cvt_pk_bf16_f32 v38, v42, v38
	v_cvt_pk_bf16_f32 v39, v43, v39
	s_waitcnt vmcnt(2)
; __device__ __forceinline__ float lo16(unsigned u) { return __uint_as_float(u << 16); }
; __device__ __forceinline__ float hi16(unsigned u) { return __uint_as_float(u & 0xffff0000u); }
; __device__ __forceinline__ unsigned pk2(float lo, float hi) { f32x2n v = {lo, hi}; bf16x2n b = __builtin_convertvector(v, bf16x2n); return __builtin_bit_cast(unsigned, b); }
; __device__ __forceinline__ float sigm(float x) { return __builtin_amdgcn_rcpf(1.f + __expf(-x)); }
; __device__ __forceinline__ float tanh_fast(float x) { float e = __expf(2.f * x); return 1.f - 2.f * __builtin_amdgcn_rcpf(e + 1.f); }
; #define p (kparams())
; #define ws (kparams()->ws)
; template <int MODE>
; __device__ __forceinline__ bf16x8 xf_frag(const bf16_t* p) {
;   const u32x4 u = *(const u32x4*)p;
;   if (MODE == 0) return __builtin_bit_cast(bf16x8, u);
;   float f[8] = {lo16(u.x), hi16(u.x), lo16(u.y), hi16(u.y), lo16(u.z), hi16(u.z), lo16(u.w), hi16(u.w)};
; #pragma unroll
;   for (int e = 0; e < 8; ++e) f[e] = MODE == 1 ? tanh_fast(f[e]) : sigm(f[e]);
;   u32x4 o; o.x = pk2(f[0], f[1]); o.y = pk2(f[2], f[3]); o.z = pk2(f[4], f[5]); o.w = pk2(f[6], f[7]);
;   return __builtin_bit_cast(bf16x8, o);
; __device__ __forceinline__ void rwkv_prep_item(const int wv_, KPR p, int l, int item, bf16_t* tile) {
;     ...
;     for (int ks = 0; ks < 2; ++ks) { aw[d][ks] = xf_frag<1>(arow + O_WL + d * 64 + ks * 32 + tq * 8); aa[d][ks] = xf_frag<0>(arow + O_AL + d * 64 + ks * 32 + tq * 8); }
; #pragma unroll
;   for (int ks = 0; ks < 4; ++ks) ag[ks] = xf_frag<2>(arow + O_GL + ks * 32 + tq * 8);
;   const bf16_t* W2T = (const bf16_t*)(p->ws + WS_SW); const bf16_t* A2T = W2T + 65536; const bf16_t* G2T = W2T + 131072;
;   bf16_t* PRE = (bf16_t*)(p->ws + R_PRE);
;   const size_t AE = (size_t)T * 512;
;     ...
;     const float kkw = p->in[I_RWKK][l * C + c];
;     const float ka = p->in[I_RWKA][l * C + c];
;     const float w00 = p->in[I_RWW0][(l * 2 + 0) * C + c], w01 = p->in[I_RWW0][(l * 2 + 1) * C + c];
;     const float a00 = p->in[I_RWA0][(l * 2 + 0) * C + c], a01 = p->in[I_RWA0][(l * 2 + 1) * C + c];
	v_mov_b64_e32 v[40:41], v[226:227]
	v_mov_b64_e32 v[42:43], v[228:229]
	v_lshlrev_b32_e32 v44, 16, v40
	v_and_b32_e32 v40, 0xffff0000, v40
	v_lshlrev_b32_e32 v45, 16, v41
	v_and_b32_e32 v41, 0xffff0000, v41
	v_lshlrev_b32_e32 v46, 16, v42
	v_and_b32_e32 v42, 0xffff0000, v42
	v_lshlrev_b32_e32 v47, 16, v43
	v_and_b32_e32 v43, 0xffff0000, v43
	v_mul_f32_e32 v44, 0xbfb8aa3b, v44
	v_mul_f32_e32 v40, 0xbfb8aa3b, v40
	v_mul_f32_e32 v45, 0xbfb8aa3b, v45
	v_mul_f32_e32 v41, 0xbfb8aa3b, v41
	v_mul_f32_e32 v46, 0xbfb8aa3b, v46
	v_mul_f32_e32 v42, 0xbfb8aa3b, v42
	v_mul_f32_e32 v47, 0xbfb8aa3b, v47
	v_mul_f32_e32 v43, 0xbfb8aa3b, v43
	v_exp_f32_e32 v44, v44
	v_exp_f32_e32 v40, v40
	v_exp_f32_e32 v45, v45
	v_exp_f32_e32 v41, v41
	v_exp_f32_e32 v46, v46
	v_exp_f32_e32 v42, v42
	v_exp_f32_e32 v47, v47
	v_exp_f32_e32 v43, v43
	v_add_f32_e32 v44, 1.0, v44
	v_add_f32_e32 v40, 1.0, v40
	v_add_f32_e32 v45, 1.0, v45
	v_add_f32_e32 v41, 1.0, v41
	v_add_f32_e32 v46, 1.0, v46
	v_add_f32_e32 v42, 1.0, v42
	v_add_f32_e32 v47, 1.0, v47
	v_add_f32_e32 v43, 1.0, v43
	v_rcp_f32_e32 v44, v44
	v_rcp_f32_e32 v40, v40
	v_rcp_f32_e32 v45, v45
	v_rcp_f32_e32 v41, v41
	v_rcp_f32_e32 v46, v46
	v_rcp_f32_e32 v42, v42
	v_rcp_f32_e32 v47, v47
	v_rcp_f32_e32 v43, v43
	v_cvt_pk_bf16_f32 v40, v44, v40
	v_cvt_pk_bf16_f32 v41, v45, v41
	v_cvt_pk_bf16_f32 v42, v46, v42
	v_cvt_pk_bf16_f32 v43, v47, v43
	s_waitcnt vmcnt(1)
	v_mov_b64_e32 v[44:45], v[230:231]
	v_mov_b64_e32 v[46:47], v[232:233]
	v_lshlrev_b32_e32 v50, 16, v44
	v_and_b32_e32 v44, 0xffff0000, v44
	v_lshlrev_b32_e32 v51, 16, v45
	v_and_b32_e32 v45, 0xffff0000, v45
	v_mul_f32_e32 v50, 0xbfb8aa3b, v50
	v_mul_f32_e32 v44, 0xbfb8aa3b, v44
	v_mul_f32_e32 v51, 0xbfb8aa3b, v51
	v_mul_f32_e32 v45, 0xbfb8aa3b, v45
	v_exp_f32_e32 v50, v50
	v_exp_f32_e32 v44, v44
	v_exp_f32_e32 v51, v51
	v_exp_f32_e32 v45, v45
	v_add_f32_e32 v50, 1.0, v50
	v_add_f32_e32 v44, 1.0, v44
	v_add_f32_e32 v51, 1.0, v51
	v_add_f32_e32 v45, 1.0, v45
	v_rcp_f32_e32 v50, v50
	v_rcp_f32_e32 v44, v44
	v_rcp_f32_e32 v51, v51
	v_rcp_f32_e32 v45, v45
	v_lshlrev_b32_e32 v62, 16, v46
	v_cvt_pk_bf16_f32 v44, v50, v44
	v_and_b32_e32 v46, 0xffff0000, v46
	v_cvt_pk_bf16_f32 v45, v51, v45
	s_waitcnt vmcnt(0)
	v_mov_b64_e32 v[48:49], v[234:235]
	v_mov_b64_e32 v[50:51], v[236:237]
	v_lshlrev_b32_e32 v63, 16, v47
	v_and_b32_e32 v47, 0xffff0000, v47
	v_mul_f32_e32 v62, 0xbfb8aa3b, v62
	v_mul_f32_e32 v46, 0xbfb8aa3b, v46
	v_mul_f32_e32 v63, 0xbfb8aa3b, v63
	v_mul_f32_e32 v47, 0xbfb8aa3b, v47
	v_exp_f32_e32 v62, v62
	v_exp_f32_e32 v46, v46
	v_exp_f32_e32 v63, v63
	v_exp_f32_e32 v47, v47
	v_add_f32_e32 v62, 1.0, v62
	v_add_f32_e32 v46, 1.0, v46
	v_add_f32_e32 v63, 1.0, v63
	v_add_f32_e32 v47, 1.0, v47
	v_rcp_f32_e32 v62, v62
	v_rcp_f32_e32 v46, v46
	v_rcp_f32_e32 v63, v63
	v_rcp_f32_e32 v47, v47
	v_cvt_pk_bf16_f32 v46, v62, v46
	v_cvt_pk_bf16_f32 v47, v63, v47
	v_lshlrev_b32_e32 v62, 16, v48
	v_and_b32_e32 v48, 0xffff0000, v48
	v_lshlrev_b32_e32 v63, 16, v49
	v_and_b32_e32 v49, 0xffff0000, v49
	v_mul_f32_e32 v62, 0xbfb8aa3b, v62
	v_mul_f32_e32 v48, 0xbfb8aa3b, v48
	v_mul_f32_e32 v63, 0xbfb8aa3b, v63
	v_mul_f32_e32 v49, 0xbfb8aa3b, v49
	v_exp_f32_e32 v62, v62
	v_exp_f32_e32 v48, v48
	v_exp_f32_e32 v63, v63
	v_exp_f32_e32 v49, v49
	v_add_f32_e32 v62, 1.0, v62
	v_add_f32_e32 v48, 1.0, v48
	v_add_f32_e32 v63, 1.0, v63
	v_add_f32_e32 v49, 1.0, v49
	v_rcp_f32_e32 v62, v62
	v_rcp_f32_e32 v48, v48
	v_rcp_f32_e32 v63, v63
	v_rcp_f32_e32 v49, v49
	v_lshlrev_b32_e32 v64, 16, v50
	v_and_b32_e32 v50, 0xffff0000, v50
	v_lshlrev_b32_e32 v65, 16, v51
	v_and_b32_e32 v51, 0xffff0000, v51
	v_mul_f32_e32 v64, 0xbfb8aa3b, v64
	v_mul_f32_e32 v50, 0xbfb8aa3b, v50
	v_mul_f32_e32 v65, 0xbfb8aa3b, v65
	v_mul_f32_e32 v51, 0xbfb8aa3b, v51
	v_exp_f32_e32 v64, v64
	v_exp_f32_e32 v50, v50
	v_exp_f32_e32 v65, v65
	v_exp_f32_e32 v51, v51
	v_cvt_pk_bf16_f32 v48, v62, v48
	v_cvt_pk_bf16_f32 v49, v63, v49
	v_lshl_add_u64 v[62:63], s[14:15], 0, v[0:1]
	s_mov_b64 s[14:15], 0x1080000
	v_lshl_add_u64 v[0:1], v[62:63], 0, s[14:15]
	s_mov_b64 s[14:15], 0x10a0000
	v_lshl_add_u64 v[72:73], v[62:63], 0, s[14:15]
	s_mov_b64 s[14:15], 0x10c0000
	v_add_f32_e32 v64, 1.0, v64
	v_add_f32_e32 v50, 1.0, v50
	v_add_f32_e32 v65, 1.0, v65
	v_add_f32_e32 v51, 1.0, v51
	v_lshl_add_u64 v[74:75], v[62:63], 0, s[14:15]
	s_load_dwordx2 s[14:15], s[12:13], 0x58
	s_load_dwordx2 s[18:19], s[12:13], 0x68
	s_nop 0
	s_load_dwordx2 s[12:13], s[12:13], 0x88
	v_rcp_f32_e32 v64, v64
	v_rcp_f32_e32 v50, v50
	v_rcp_f32_e32 v65, v65
	v_rcp_f32_e32 v51, v51
	v_cvt_pk_bf16_f32 v50, v64, v50
	v_cvt_pk_bf16_f32 v51, v65, v51
; __device__ __forceinline__ float bf2f(bf16_t h) { return __uint_as_float((unsigned)h << 16); }
; __device__ __forceinline__ void conv4(const bf16_t* tile, const float* cw, int ch, int tq, float (&o)[4]) {
;   const float w0 = cw[ch], w1 = cw[1536 + ch], w2 = cw[3072 + ch];
;   float xs[6];
; #pragma unroll
;   for (int i = 0; i < 6; ++i) xs[i] = bf2f(tile[(tq * 4 + i) * RPS + ch]);
; #pragma unroll
;   for (int j = 0; j < 4; ++j) o[j] = w0 * xs[j] + w1 * xs[j + 1] + w2 * xs[j + 2];
; }
; __device__ __forceinline__ void rwkv_prep_item(const int wv_, KPR p, int l, int item, bf16_t* tile) {
;     ...
;   for (int nt = 0; nt < 4; ++nt) { const int c = wid * 64 + nt * 16 + cl;
;     f32x4 accw[2], acca[2], accg = (f32x4){0.f, 0.f, 0.f, 0.f};
; #pragma unroll
;     for (int d = 0; d < 2; ++d) { accw[d] = (f32x4){0.f, 0.f, 0.f, 0.f}; acca[d] = (f32x4){0.f, 0.f, 0.f, 0.f};
; #pragma unroll
;       for (int ks = 0; ks < 2; ++ks) {
;         accw[d] = __builtin_amdgcn_mfma_f32_16x16x32_bf16(aw[d][ks], ld_frag(W2T + ((size_t)d * C + c) * 64 + ks * 32 + tq * 8), accw[d], 0, 0, 0);
;         acca[d] = __builtin_amdgcn_mfma_f32_16x16x32_bf16(aa[d][ks], ld_frag(A2T + ((size_t)d * C + c) * 64 + ks * 32 + tq * 8), acca[d], 0, 0, 0); } }
; #pragma unroll
;     for (int ks = 0; ks < 4; ++ks) accg = __builtin_amdgcn_mfma_f32_16x16x32_bf16(ag[ks], ld_frag(G2T + (size_t)c * 128 + ks * 32 + tq * 8), accg, 0, 0, 0);
;     float r4[4], k4[4], v4[4]; conv4(tile, cw, c, tq, r4); conv4(tile, cw, 512 + c, tq, k4); conv4(tile, cw, 1024 + c, tq, v4);
.LBB0_477:
	v_ashrrev_i32_e32 v85, 31, v84
	v_lshlrev_b64 v[52:53], 7, v[84:85]
	v_lshl_add_u64 v[90:91], v[0:1], 0, v[52:53]
	v_lshl_add_u64 v[92:93], v[72:73], 0, v[52:53]
	v_lshl_add_u64 v[238:239], v[90:91], 0, s[92:93]
	v_lshl_add_u64 v[240:241], v[92:93], 0, s[92:93]
	v_lshlrev_b64 v[52:53], 8, v[84:85]
	v_lshl_add_u64 v[124:125], v[74:75], 0, v[52:53]
	global_load_dwordx4 v[190:193], v[90:91], off
	global_load_dwordx4 v[194:197], v[90:91], off offset:64
	global_load_dwordx4 v[198:201], v[92:93], off
	global_load_dwordx4 v[202:205], v[92:93], off offset:64
	global_load_dwordx4 v[206:209], v[238:239], off
	global_load_dwordx4 v[210:213], v[238:239], off offset:64
	global_load_dwordx4 v[214:217], v[240:241], off
	global_load_dwordx4 v[218:221], v[240:241], off offset:64
	global_load_dwordx4 v[222:225], v[124:125], off
	global_load_dwordx4 v[226:229], v[124:125], off offset:64
	global_load_dwordx4 v[230:233], v[124:125], off offset:128
	global_load_dwordx4 v[234:237], v[124:125], off offset:192
	v_add_u32_e32 v106, s20, v3
	s_add_i32 s20, s20, 32
	s_cmpk_lg_i32 s20, 0x80
	s_waitcnt vmcnt(11)
	v_mfma_f32_16x16x32_bf16 v[68:71], v[4:7], v[190:193], 0
	s_waitcnt vmcnt(10)
	v_mfma_f32_16x16x32_bf16 v[68:71], v[12:15], v[194:197], v[68:71]
	s_waitcnt vmcnt(9)
	v_mfma_f32_16x16x32_bf16 v[64:67], v[8:11], v[198:201], 0
	s_waitcnt vmcnt(8)
	v_mfma_f32_16x16x32_bf16 v[64:67], v[16:19], v[202:205], v[64:67]
	s_waitcnt vmcnt(7)
	v_mfma_f32_16x16x32_bf16 v[60:63], v[20:23], v[206:209], 0
	s_waitcnt vmcnt(6)
	v_mfma_f32_16x16x32_bf16 v[60:63], v[28:31], v[210:213], v[60:63]
	s_waitcnt vmcnt(5)
	v_mfma_f32_16x16x32_bf16 v[56:59], v[24:27], v[214:217], 0
	s_waitcnt vmcnt(4)
	v_mfma_f32_16x16x32_bf16 v[56:59], v[32:35], v[218:221], v[56:59]
	s_waitcnt vmcnt(3)
	v_mfma_f32_16x16x32_bf16 v[52:55], v[36:39], v[222:225], 0
	s_waitcnt vmcnt(2)
	v_mfma_f32_16x16x32_bf16 v[52:55], v[40:43], v[226:229], v[52:55]
	s_waitcnt vmcnt(1)
	v_mfma_f32_16x16x32_bf16 v[52:55], v[44:47], v[230:233], v[52:55]
	v_lshl_add_u64 v[94:95], v[84:85], 2, s[4:5]
	v_add_co_u32_e32 v96, vcc, s52, v94
	s_waitcnt vmcnt(0)
	v_mfma_f32_16x16x32_bf16 v[52:55], v[48:51], v[234:237], v[52:55]
	v_addc_co_u32_e32 v97, vcc, 0, v95, vcc
	global_load_dword v93, v[96:97], off offset:2048
	global_load_dword v91, v[94:95], off
	ds_read_u16 v92, v106
	v_add_co_u32_e32 v100, vcc, s54, v94
	s_nop 2
	v_cvt_f16_f32_e32 v52, v52
	v_addc_co_u32_e32 v101, vcc, 0, v95, vcc
	s_waitcnt lgkmcnt(0)
	v_lshlrev_b32_e32 v99, 16, v92
	ds_read_u16 v92, v106 offset:3104
	v_add_co_u32_e32 v102, vcc, s80, v94
	v_cvt_f16_f32_e32 v54, v54
	s_nop 0
	v_addc_co_u32_e32 v103, vcc, 0, v95, vcc
	s_waitcnt lgkmcnt(0)
	v_lshlrev_b32_e32 v104, 16, v92
	ds_read_u16 v92, v106 offset:6208
	global_load_dword v90, v[102:103], off offset:-4096
	global_load_dword v111, v[94:95], off offset:2048
	s_waitcnt lgkmcnt(0)
	v_lshlrev_b32_e32 v107, 16, v92
	ds_read_u16 v92, v106 offset:9312
	s_waitcnt lgkmcnt(0)
	v_lshlrev_b32_e32 v108, 16, v92
	ds_read_u16 v92, v106 offset:12416
	s_waitcnt lgkmcnt(0)
	v_lshlrev_b32_e32 v98, 16, v92
	ds_read_u16 v92, v106 offset:15520
	s_waitcnt lgkmcnt(0)
	v_lshlrev_b32_e32 v92, 16, v92
	s_waitcnt vmcnt(3)
	v_mul_f32_e32 v110, v93, v107
	v_mul_f32_e32 v109, v93, v104
	s_waitcnt vmcnt(2)
	v_fmac_f32_e32 v110, v91, v104
	v_add_co_u32_e32 v104, vcc, s63, v94
	v_fmac_f32_e32 v109, v91, v99
	v_mul_f32_e32 v99, v93, v108
	v_mul_f32_e32 v93, v93, v98
	v_addc_co_u32_e32 v105, vcc, 0, v95, vcc
	v_fmac_f32_e32 v99, v91, v107
	v_fmac_f32_e32 v93, v91, v108
	global_load_dword v91, v[104:105], off
	global_load_dword v94, v[100:101], off offset:2048
	ds_read_u16 v95, v106 offset:1024
	ds_read_u16 v100, v106 offset:4128
	s_waitcnt vmcnt(3)
	v_fma_mixlo_f16 v107, v90, v107, v109
	s_waitcnt lgkmcnt(1)
	v_lshlrev_b32_e32 v95, 16, v95
	s_waitcnt lgkmcnt(0)
	v_lshlrev_b32_e32 v101, 16, v100
	ds_read_u16 v100, v106 offset:7232
	s_waitcnt lgkmcnt(0)
	v_lshlrev_b32_e32 v112, 16, v100
	ds_read_u16 v100, v106 offset:10336
	s_waitcnt lgkmcnt(0)
	v_lshlrev_b32_e32 v113, 16, v100
	ds_read_u16 v100, v106 offset:13440
	s_waitcnt lgkmcnt(0)
	v_lshlrev_b32_e32 v114, 16, v100
	ds_read_u16 v100, v106 offset:16544
	s_waitcnt lgkmcnt(0)
	v_lshlrev_b32_e32 v115, 16, v100
	s_waitcnt vmcnt(1)
	v_mul_f32_e32 v116, v91, v101
	v_fmac_f32_e32 v116, v111, v95
	v_mul_f32_e32 v100, v91, v112
	v_mul_f32_e32 v95, v91, v113
	v_mul_f32_e32 v91, v91, v114
	v_fmac_f32_e32 v100, v111, v101
	v_fmac_f32_e32 v95, v111, v112
	v_fmac_f32_e32 v91, v111, v113
	s_waitcnt vmcnt(0)
	v_fmac_f32_e32 v116, v94, v112
	v_fmac_f32_e32 v100, v94, v113
	v_fmac_f32_e32 v95, v94, v114
	v_fmac_f32_e32 v91, v94, v115
	global_load_dword v111, v[96:97], off
	s_nop 0
	global_load_dword v97, v[104:105], off offset:2048
	global_load_dword v94, v[102:103], off
	ds_read_u16 v96, v106 offset:2048
	s_waitcnt lgkmcnt(0)
	v_lshlrev_b32_e32 v102, 16, v96
	ds_read_u16 v96, v106 offset:5152
	s_waitcnt lgkmcnt(0)
	v_lshlrev_b32_e32 v103, 16, v96
	ds_read_u16 v96, v106 offset:8256
	s_waitcnt lgkmcnt(0)
	v_lshlrev_b32_e32 v112, 16, v96
	ds_read_u16 v96, v106 offset:11360
	s_waitcnt lgkmcnt(0)
	v_lshlrev_b32_e32 v113, 16, v96
	ds_read_u16 v96, v106 offset:14464
	s_waitcnt lgkmcnt(0)
	v_lshlrev_b32_e32 v101, 16, v96
	ds_read_u16 v96, v106 offset:17568
	s_waitcnt lgkmcnt(0)
	v_lshlrev_b32_e32 v96, 16, v96
	s_waitcnt vmcnt(1)
; __device__ __forceinline__ float sigm(float x) { return __builtin_amdgcn_rcpf(1.f + __expf(-x)); }
; #define p (kparams())
; __device__ __forceinline__ void rwkv_prep_item(const int wv_, KPR p, int l, int item, bf16_t* tile) {
;     ...
;     float r4[4], k4[4], v4[4]; conv4(tile, cw, c, tq, r4); conv4(tile, cw, 512 + c, tq, k4); conv4(tile, cw, 1024 + c, tq, v4);
;     const float kkw = p->in[I_RWKK][l * C + c];
;     const float ka = p->in[I_RWKA][l * C + c];
;     const float w00 = p->in[I_RWW0][(l * 2 + 0) * C + c], w01 = p->in[I_RWW0][(l * 2 + 1) * C + c];
;     const float a00 = p->in[I_RWA0][(l * 2 + 0) * C + c], a01 = p->in[I_RWA0][(l * 2 + 1) * C + c];
; #pragma unroll
;     for (int j = 0; j < 4; ++j) { const size_t o = (size_t)(R0 + tq * 4 + j) * 512 + c;
;       const float kn = k4[j] * kkw * inv[j];
;       PRE[0 * AE + o] = f2h(r4[j]); PRE[1 * AE + o] = f2h(v4[j]); PRE[2 * AE + o] = f2h(kn);
; #pragma unroll
;       for (int d = 0; d < 2; ++d) { const float wpre = (d == 0 ? w00 : w01) + accw[d][j];
;         const float u = 1.f - __expf(-0.6065306597f * sigm(wpre));
;         const float a = sigm((d == 0 ? a00 : a01) + acca[d][j]);
;         PRE[(3 + d) * AE + o] = f2h(u); PRE[(5 + d) * AE + o] = f2h(kn * a); PRE[(7 + d) * AE + o] = f2h(k4[j] * (1.f + (a - 1.f) * ka)); }
;       PRE[9 * AE + o] = f2h(accg[j]); } }
	v_mul_f32_e32 v106, v97, v103
	v_fmac_f32_e32 v106, v111, v102
	v_mul_f32_e32 v114, v97, v112
	v_add_u32_e32 v102, s78, v84
	v_fmac_f32_e32 v114, v111, v103
	v_ashrrev_i32_e32 v103, 31, v102
	v_lshlrev_b64 v[102:103], 2, v[102:103]
	v_lshl_add_u64 v[104:105], s[10:11], 0, v[102:103]
	v_lshl_add_u64 v[102:103], s[12:13], 0, v[102:103]
	global_load_dword v117, v[102:103], off
	v_add_u32_e32 v102, s9, v84
	v_ashrrev_i32_e32 v103, 31, v102
	v_mul_f32_e32 v115, v97, v113
	v_mul_f32_e32 v97, v97, v101
	v_lshlrev_b64 v[102:103], 2, v[102:103]
	v_fmac_f32_e32 v115, v111, v112
	v_fmac_f32_e32 v97, v111, v113
	global_load_dword v111, v[104:105], off
	v_lshl_add_u64 v[104:105], s[14:15], 0, v[102:103]
	global_load_dword v118, v[104:105], off
	global_load_dword v119, v[104:105], off offset:2048
	v_lshl_add_u64 v[102:103], s[18:19], 0, v[102:103]
	global_load_dword v120, v[102:103], off
	global_load_dword v121, v[102:103], off offset:2048
	v_lshl_add_u64 v[102:103], v[84:85], 1, s[16:17]
	v_lshl_add_u64 v[104:105], v[102:103], 0, v[76:77]
	s_waitcnt vmcnt(6)
	v_fma_mixlo_f16 v109, v94, v112, v106
	v_add_co_u32_e32 v106, vcc, s55, v104
	global_store_short v[104:105], v107, off
	s_nop 0
	v_addc_co_u32_e32 v107, vcc, 0, v105, vcc
	global_store_short v[106:107], v109, off
	v_add_co_u32_e32 v106, vcc, s48, v104
	v_add_u32_e32 v84, 16, v84
	s_nop 0
	v_addc_co_u32_e32 v107, vcc, 0, v105, vcc
	s_waitcnt vmcnt(6)
	v_mul_f32_e32 v85, v116, v111
	s_waitcnt vmcnt(5)
	v_add_f32_e32 v68, v68, v118
	v_mul_f32_e32 v68, 0xbfb8aa3b, v68
	v_exp_f32_e32 v68, v68
	s_waitcnt vmcnt(4)
	v_add_f32_e32 v60, v60, v119
	v_mul_f32_e32 v60, 0xbfb8aa3b, v60
	v_exp_f32_e32 v60, v60
	v_add_f32_e32 v68, 1.0, v68
	v_rcp_f32_e32 v68, v68
	s_waitcnt vmcnt(3)
	v_add_f32_e32 v64, v64, v120
	v_add_f32_e32 v60, 1.0, v60
	v_mul_f32_e32 v64, 0xbfb8aa3b, v64
	v_mul_f32_e32 v68, 0xbf1b4598, v68
	v_mul_f32_e32 v68, 0x3fb8aa3b, v68
	v_exp_f32_e32 v68, v68
	v_rcp_f32_e32 v60, v60
	v_exp_f32_e32 v64, v64
	s_waitcnt vmcnt(2)
	v_add_f32_e32 v56, v56, v121
	v_sub_f32_e32 v68, 1.0, v68
	v_mul_f32_e32 v60, 0xbf1b4598, v60
	v_add_f32_e32 v64, 1.0, v64
	v_cvt_f16_f32_e32 v68, v68
	v_mul_f32_e32 v60, 0x3fb8aa3b, v60
	v_mul_f32_e32 v122, v89, v85
	v_fma_mixlo_f16 v85, v89, v85, 0
	v_rcp_f32_e32 v64, v64
	v_exp_f32_e32 v60, v60
	v_mul_f32_e32 v56, 0xbfb8aa3b, v56
	global_store_short v[106:107], v85, off
	v_add_co_u32_e32 v106, vcc, s49, v104
	v_exp_f32_e32 v56, v56
	s_nop 0
	v_addc_co_u32_e32 v107, vcc, 0, v105, vcc
	global_store_short v[106:107], v68, off
	v_add_co_u32_e32 v106, vcc, s60, v104
	v_fma_mixlo_f16 v68, v122, v64, 0
	s_nop 0
	v_addc_co_u32_e32 v107, vcc, 0, v105, vcc
	v_add_f32_e32 v64, -1.0, v64
	v_sub_f32_e32 v60, 1.0, v60
	global_store_short v[106:107], v68, off
	v_fma_f32 v64, v117, v64, 1.0
	v_add_co_u32_e32 v106, vcc, s61, v104
	v_add_f32_e32 v56, 1.0, v56
	v_cvt_f16_f32_e32 v60, v60
	v_fma_mixlo_f16 v64, v116, v64, 0
	v_addc_co_u32_e32 v107, vcc, 0, v105, vcc
	v_rcp_f32_e32 v56, v56
	global_store_short v[106:107], v64, off
	v_add_co_u32_e32 v106, vcc, s3, v104
	s_nop 1
	v_addc_co_u32_e32 v107, vcc, 0, v105, vcc
	global_store_short v[106:107], v60, off
	v_add_co_u32_e32 v106, vcc, s74, v104
	v_fma_mixlo_f16 v60, v122, v56, 0
	s_nop 0
	v_addc_co_u32_e32 v107, vcc, 0, v105, vcc
	global_store_short v[106:107], v60, off
	v_add_co_u32_e32 v106, vcc, s65, v104
	v_add_f32_e32 v56, -1.0, v56
	s_nop 0
	v_addc_co_u32_e32 v107, vcc, 0, v105, vcc
	v_add_co_u32_e32 v104, vcc, s62, v104
	v_fma_f32 v56, v117, v56, 1.0
	s_nop 0
	v_addc_co_u32_e32 v105, vcc, 0, v105, vcc
	v_fma_mixlo_f16 v56, v116, v56, 0
	global_store_short v[104:105], v52, off
	v_lshl_add_u64 v[104:105], v[102:103], 0, v[78:79]
	global_store_short v[106:107], v56, off
	v_fma_mixlo_f16 v56, v90, v108, v110
	v_add_co_u32_e32 v106, vcc, s55, v104
	global_store_short v[104:105], v56, off
	v_fma_mixlo_f16 v56, v94, v113, v114
	v_addc_co_u32_e32 v107, vcc, 0, v105, vcc
	v_mul_f32_e32 v52, v100, v111
	global_store_short v[106:107], v56, off
	v_add_co_u32_e32 v106, vcc, s48, v104
	v_mul_f32_e32 v60, v88, v52
	v_fma_mixlo_f16 v52, v88, v52, 0
	v_addc_co_u32_e32 v107, vcc, 0, v105, vcc
	global_store_short v[106:107], v52, off
	v_add_f32_e32 v52, v69, v118
	v_mul_f32_e32 v52, 0xbfb8aa3b, v52
	v_exp_f32_e32 v52, v52
	v_add_f32_e32 v56, v65, v120
	v_mul_f32_e32 v56, 0xbfb8aa3b, v56
	v_exp_f32_e32 v56, v56
	v_add_f32_e32 v52, 1.0, v52
	v_rcp_f32_e32 v52, v52
	v_add_co_u32_e32 v64, vcc, s49, v104
	v_add_f32_e32 v56, 1.0, v56
	v_mul_f32_e32 v52, 0xbf1b4598, v52
	v_mul_f32_e32 v52, 0x3fb8aa3b, v52
	v_exp_f32_e32 v52, v52
	v_rcp_f32_e32 v56, v56
	v_addc_co_u32_e32 v65, vcc, 0, v105, vcc
	v_sub_f32_e32 v52, 1.0, v52
	v_cvt_f16_f32_e32 v52, v52
	global_store_short v[64:65], v52, off
	v_add_co_u32_e32 v64, vcc, s60, v104
	v_fma_mixlo_f16 v52, v60, v56, 0
	s_nop 0
	v_addc_co_u32_e32 v65, vcc, 0, v105, vcc
	global_store_short v[64:65], v52, off
	v_add_f32_e32 v52, -1.0, v56
	v_fma_f32 v52, v117, v52, 1.0
	v_add_co_u32_e32 v64, vcc, s61, v104
	v_fma_mixlo_f16 v52, v100, v52, 0
	s_nop 0
	v_addc_co_u32_e32 v65, vcc, 0, v105, vcc
	global_store_short v[64:65], v52, off
	v_add_f32_e32 v52, v61, v119
	v_mul_f32_e32 v52, 0xbfb8aa3b, v52
	v_exp_f32_e32 v52, v52
	v_add_f32_e32 v56, v57, v121
	v_mul_f32_e32 v56, 0xbfb8aa3b, v56
	v_exp_f32_e32 v56, v56
	v_add_f32_e32 v52, 1.0, v52
	v_rcp_f32_e32 v52, v52
	v_fma_mixlo_f16 v64, v94, v101, v115
	v_add_f32_e32 v56, 1.0, v56
	v_rcp_f32_e32 v61, v56
	v_mul_f32_e32 v52, 0xbf1b4598, v52
	v_mul_f32_e32 v52, 0x3fb8aa3b, v52
	v_exp_f32_e32 v52, v52
	v_add_co_u32_e32 v56, vcc, s3, v104
	v_sub_f32_e32 v52, 1.0, v52
	v_cvt_f16_f32_e32 v52, v52
; __device__ __forceinline__ float sigm(float x) { return __builtin_amdgcn_rcpf(1.f + __expf(-x)); }
; __device__ __forceinline__ void rwkv_prep_item(const int wv_, KPR p, int l, int item, bf16_t* tile) {
;     ...
; #pragma unroll
;     for (int j = 0; j < 4; ++j) { const size_t o = (size_t)(R0 + tq * 4 + j) * 512 + c;
;       const float kn = k4[j] * kkw * inv[j];
;       PRE[0 * AE + o] = f2h(r4[j]); PRE[1 * AE + o] = f2h(v4[j]); PRE[2 * AE + o] = f2h(kn);
; #pragma unroll
;       for (int d = 0; d < 2; ++d) { const float wpre = (d == 0 ? w00 : w01) + accw[d][j];
;         const float u = 1.f - __expf(-0.6065306597f * sigm(wpre));
;         const float a = sigm((d == 0 ? a00 : a01) + acca[d][j]);
;         PRE[(3 + d) * AE + o] = f2h(u); PRE[(5 + d) * AE + o] = f2h(kn * a); PRE[(7 + d) * AE + o] = f2h(k4[j] * (1.f + (a - 1.f) * ka)); }
;       PRE[9 * AE + o] = f2h(accg[j]); } }
	v_addc_co_u32_e32 v57, vcc, 0, v105, vcc
	global_store_short v[56:57], v52, off
	v_add_co_u32_e32 v56, vcc, s74, v104
	v_fma_mixlo_f16 v52, v60, v61, 0
	s_nop 0
	v_addc_co_u32_e32 v57, vcc, 0, v105, vcc
	global_store_short v[56:57], v52, off
	v_add_f32_e32 v52, -1.0, v61
	v_fma_f32 v52, v117, v52, 1.0
	v_add_co_u32_e32 v56, vcc, s65, v104
	v_fma_mixlo_f16 v52, v100, v52, 0
	s_nop 0
	v_addc_co_u32_e32 v57, vcc, 0, v105, vcc
	global_store_short v[56:57], v52, off
	v_cvt_f16_f32_e32 v56, v53
	v_add_co_u32_e32 v52, vcc, s62, v104
	v_mul_f32_e32 v60, v95, v111
	s_nop 0
	v_addc_co_u32_e32 v53, vcc, 0, v105, vcc
	global_store_short v[52:53], v56, off
	v_fma_mixlo_f16 v56, v90, v98, v99
	v_lshl_add_u64 v[52:53], v[102:103], 0, v[80:81]
	global_store_short v[52:53], v56, off
	v_add_co_u32_e32 v56, vcc, s55, v52
	v_mul_f32_e32 v61, v87, v60
	s_nop 0
	v_addc_co_u32_e32 v57, vcc, 0, v53, vcc
	global_store_short v[56:57], v64, off
	v_add_co_u32_e32 v56, vcc, s48, v52
	v_fma_mixlo_f16 v60, v87, v60, 0
	s_nop 0
	v_addc_co_u32_e32 v57, vcc, 0, v53, vcc
	global_store_short v[56:57], v60, off
	v_add_f32_e32 v56, v70, v118
	v_mul_f32_e32 v56, 0xbfb8aa3b, v56
	v_exp_f32_e32 v56, v56
	v_add_f32_e32 v57, v66, v120
	v_mul_f32_e32 v57, 0xbfb8aa3b, v57
	v_exp_f32_e32 v57, v57
	v_add_f32_e32 v56, 1.0, v56
	v_rcp_f32_e32 v56, v56
	v_add_f32_e32 v57, 1.0, v57
	v_rcp_f32_e32 v60, v57
	v_mul_f32_e32 v56, 0xbf1b4598, v56
	v_mul_f32_e32 v56, 0x3fb8aa3b, v56
	v_exp_f32_e32 v56, v56
	s_nop 0
	v_sub_f32_e32 v56, 1.0, v56
	v_cvt_f16_f32_e32 v64, v56
	v_add_co_u32_e32 v56, vcc, s49, v52
	s_nop 1
	v_addc_co_u32_e32 v57, vcc, 0, v53, vcc
	global_store_short v[56:57], v64, off
	v_add_co_u32_e32 v56, vcc, s60, v52
	v_fma_mixlo_f16 v64, v61, v60, 0
	s_nop 0
	v_addc_co_u32_e32 v57, vcc, 0, v53, vcc
	global_store_short v[56:57], v64, off
	v_add_f32_e32 v56, -1.0, v60
	v_fma_f32 v56, v117, v56, 1.0
	v_fma_mixlo_f16 v60, v95, v56, 0
	v_add_co_u32_e32 v56, vcc, s61, v52
	s_nop 1
	v_addc_co_u32_e32 v57, vcc, 0, v53, vcc
	global_store_short v[56:57], v60, off
	v_add_f32_e32 v56, v62, v119
	v_mul_f32_e32 v56, 0xbfb8aa3b, v56
	v_exp_f32_e32 v56, v56
	v_add_f32_e32 v57, v58, v121
	v_mul_f32_e32 v57, 0xbfb8aa3b, v57
	v_exp_f32_e32 v57, v57
	v_add_f32_e32 v56, 1.0, v56
	v_rcp_f32_e32 v56, v56
	v_add_f32_e32 v57, 1.0, v57
	v_rcp_f32_e32 v58, v57
	v_mul_f32_e32 v56, 0xbf1b4598, v56
	v_mul_f32_e32 v56, 0x3fb8aa3b, v56
	v_exp_f32_e32 v56, v56
	s_nop 0
	v_sub_f32_e32 v56, 1.0, v56
	v_cvt_f16_f32_e32 v60, v56
	v_add_co_u32_e32 v56, vcc, s3, v52
	s_nop 1
	v_addc_co_u32_e32 v57, vcc, 0, v53, vcc
	global_store_short v[56:57], v60, off
	v_add_co_u32_e32 v56, vcc, s74, v52
	v_fma_mixlo_f16 v60, v61, v58, 0
	s_nop 0
	v_addc_co_u32_e32 v57, vcc, 0, v53, vcc
	global_store_short v[56:57], v60, off
	v_add_f32_e32 v56, -1.0, v58
	v_fma_f32 v56, v117, v56, 1.0
	v_fma_mixlo_f16 v58, v95, v56, 0
	v_add_co_u32_e32 v56, vcc, s65, v52
	v_fma_mixlo_f16 v60, v94, v96, v97
	s_nop 0
	v_addc_co_u32_e32 v57, vcc, 0, v53, vcc
	v_add_co_u32_e32 v52, vcc, s62, v52
	global_store_short v[56:57], v58, off
	s_nop 0
	v_addc_co_u32_e32 v53, vcc, 0, v53, vcc
	global_store_short v[52:53], v54, off
	v_fma_mixlo_f16 v56, v90, v92, v93
	v_lshl_add_u64 v[52:53], v[102:103], 0, v[82:83]
	global_store_short v[52:53], v56, off
	v_add_co_u32_e32 v56, vcc, s55, v52
	v_mul_f32_e32 v54, v91, v111
	s_nop 0
	v_addc_co_u32_e32 v57, vcc, 0, v53, vcc
	global_store_short v[56:57], v60, off
	v_add_co_u32_e32 v56, vcc, s48, v52
	v_mul_f32_e32 v58, v86, v54
	v_fma_mixlo_f16 v54, v86, v54, 0
	v_addc_co_u32_e32 v57, vcc, 0, v53, vcc
	global_store_short v[56:57], v54, off
	v_add_f32_e32 v54, v71, v118
	v_mul_f32_e32 v54, 0xbfb8aa3b, v54
	v_exp_f32_e32 v54, v54
	v_add_f32_e32 v56, v67, v120
	v_mul_f32_e32 v56, 0xbfb8aa3b, v56
	v_exp_f32_e32 v56, v56
	v_add_f32_e32 v54, 1.0, v54
	v_rcp_f32_e32 v54, v54
	v_add_f32_e32 v56, 1.0, v56
	v_rcp_f32_e32 v60, v56
	v_mul_f32_e32 v54, 0xbf1b4598, v54
	v_mul_f32_e32 v54, 0x3fb8aa3b, v54
	v_exp_f32_e32 v54, v54
	v_add_co_u32_e32 v56, vcc, s49, v52
	v_sub_f32_e32 v54, 1.0, v54
	v_cvt_f16_f32_e32 v54, v54
	v_addc_co_u32_e32 v57, vcc, 0, v53, vcc
	global_store_short v[56:57], v54, off
	v_add_co_u32_e32 v56, vcc, s60, v52
	v_fma_mixlo_f16 v54, v58, v60, 0
	s_nop 0
	v_addc_co_u32_e32 v57, vcc, 0, v53, vcc
	global_store_short v[56:57], v54, off
	v_add_f32_e32 v54, -1.0, v60
	v_fma_f32 v54, v117, v54, 1.0
	v_add_co_u32_e32 v56, vcc, s61, v52
	v_fma_mixlo_f16 v54, v91, v54, 0
	s_nop 0
	v_addc_co_u32_e32 v57, vcc, 0, v53, vcc
	global_store_short v[56:57], v54, off
	v_add_f32_e32 v54, v63, v119
	v_mul_f32_e32 v54, 0xbfb8aa3b, v54
	v_exp_f32_e32 v54, v54
	v_add_f32_e32 v56, v59, v121
	v_mul_f32_e32 v56, 0xbfb8aa3b, v56
	v_exp_f32_e32 v56, v56
	v_add_f32_e32 v54, 1.0, v54
	v_rcp_f32_e32 v54, v54
	v_add_f32_e32 v56, 1.0, v56
	v_rcp_f32_e32 v59, v56
	v_mul_f32_e32 v54, 0xbf1b4598, v54
	v_mul_f32_e32 v54, 0x3fb8aa3b, v54
	v_exp_f32_e32 v54, v54
	v_add_co_u32_e32 v56, vcc, s3, v52
	v_sub_f32_e32 v54, 1.0, v54
	v_cvt_f16_f32_e32 v54, v54
	v_addc_co_u32_e32 v57, vcc, 0, v53, vcc
	global_store_short v[56:57], v54, off
	v_add_co_u32_e32 v56, vcc, s74, v52
	v_fma_mixlo_f16 v54, v58, v59, 0
	s_nop 0
	v_addc_co_u32_e32 v57, vcc, 0, v53, vcc
	global_store_short v[56:57], v54, off
	v_add_f32_e32 v54, -1.0, v59
	v_fma_f32 v54, v117, v54, 1.0
	v_add_co_u32_e32 v56, vcc, 0x8800000, v52
	v_fma_mixlo_f16 v54, v91, v54, 0
	s_nop 0
	v_addc_co_u32_e32 v57, vcc, 0, v53, vcc
	global_store_short v[56:57], v54, off
	v_cvt_f16_f32_e32 v54, v55
	v_add_co_u32_e32 v52, vcc, 0x9900000, v52
	s_nop 1
	v_addc_co_u32_e32 v53, vcc, 0, v53, vcc
	global_store_short v[52:53], v54, off
	s_cbranch_scc1 .LBB0_477
	s_add_i32 s4, s22, 0x100
	s_cmpk_gt_i32 s22, 0x33f
	s_mov_b32 s22, s4
	s_barrier
	s_cbranch_scc0 .LBB0_461
